# GEMM K-loops: non-first tiles skip 128-v_mov zero-init via peeled half-iteration with SrcC=0 (P1,P4,P5); attention band steps<12 use SrcC=0 instead of 32 v_mov
# speedup vs baseline: 1.0330x; 1.0076x over previous
; #define PG8_STAGE(bufoff, gbase, voff) do { _Pragma("unroll") for (int _i = 0; _i < 2; ++_i) \
;         __builtin_amdgcn_global_load_lds((const unsigned*)((const char*)(gbase) + (voff)[_i]), (LAS unsigned*)(lds + (bufoff) + ldsw + _i * 8192), 16, 0, 0); } while (0)
; #define PG8_LDA(dst, b, h) do { _Pragma("unroll") for (int m = 0; m < 4; ++m) _Pragma("unroll") for (int k = 0; k < 2; ++k) dst[m][k] = *(const LAS bf16x8*)(lds + PG8_SA(b, h) + aoff + m * 2048 + k * 1024); } while (0)
; #define PG8_LDB(dst, b, h) do { _Pragma("unroll") for (int n = 0; n < 2; ++n) _Pragma("unroll") for (int k = 0; k < 2; ++k) dst[n][k] = *(const LAS bf16x8*)(lds + PG8_SB(b, h) + boff + n * 2048 + k * 1024); } while (0)
; #define PG8_MMA(ai, bj, At, Bt) do { __builtin_amdgcn_s_setprio(1); _Pragma("unroll") for (int m = 0; m < 4; ++m) _Pragma("unroll") for (int n = 0; n < 2; ++n) _Pragma("unroll") for (int k = 0; k < 2; ++k) \
;         acc[ai][bj][m][n] = __builtin_amdgcn_mfma_f32_16x16x32_bf16(Bt[n][k], At[m][k], acc[ai][bj][m][n], 0, 0, 0); __builtin_amdgcn_s_setprio(0); } while (0)
; #define PG8_WAIT_V(n) asm volatile("s_waitcnt vmcnt(" #n ")" ::: "memory")
; #define PG8_WAIT_L(n) asm volatile("s_waitcnt lgkmcnt(" #n ")" ::: "memory")
; #define PG8_BAR __builtin_amdgcn_s_barrier()
; template <class Epi, int AC0, int BC0, int NT0, int AC1, int BC1, int NT1>
; __device__ __forceinline__ void gemm_phase(LAS unsigned char* lds, const Gemm g, const StaticOrder& S, const Epi& E, int tid) {
;     ...
;         for (int t = 0; t < nt; t += 2) {
;             const bool last = (t == nt - 2);
;             const char* a1 = cA + (size_t)(t + 1) * kstep;
;             const char* a2 = last ? nA : cA + (size_t)(t + 2) * kstep; const char* b2 = last ? nB : cB + (size_t)(t + 2) * kstep;
;             const char* a3 = a2 + kstep; const char* b3 = b2 + kstep;
;             PG8_LDB(B0, 0, 0); PG8_LDB(B1, 0, 1); PG8_SCHED; PG8_LDA(At, 0, 0); PG8_STAGE(PG8_SA(1, 1), a1 + hstepA, voffA);
;             PG8_WAIT_V(8); PG8_WAIT_L(0); PG8_BAR; PG8_MMA(0, 0, At, B0); PG8_MMA(0, 1, At, B1); PG8_BAR; PG8_SCHED;
;             PG8_LDA(At, 0, 1); PG8_STAGE(PG8_SB(0, 0), b2, voffB); PG8_STAGE(PG8_SB(0, 1), b2 + hstepB, voffB); PG8_STAGE(PG8_SA(0, 0), a2, voffA);
;             PG8_WAIT_V(8); PG8_WAIT_L(0); PG8_BAR; PG8_MMA(1, 0, At, B0); PG8_MMA(1, 1, At, B1); PG8_BAR; PG8_SCHED;
.Lpeel_P1:
	ds_read_b128 v[26:29], v192
	ds_read_b128 v[30:33], v192 offset:1024
	ds_read_b128 v[42:45], v192 offset:2048
	ds_read_b128 v[46:49], v192 offset:3072
	ds_read_b128 v[146:149], v193
	ds_read_b128 v[150:153], v193 offset:1024
	ds_read_b128 v[154:157], v193 offset:2048
	ds_read_b128 v[158:161], v193 offset:3072
	s_add_u32 s6, s0, 0xfffc0080
	s_addc_u32 s7, s1, -1
	s_cmp_eq_u32 s27, 12
	s_cselect_b32 s13, s3, s7
	s_cselect_b32 s12, s9, s6
	s_cselect_b32 s7, s11, s22
	s_cselect_b32 s6, s15, s16
	v_lshl_add_u64 v[186:187], s[0:1], 0, v[178:179]
	s_add_i32 m0, s95, 0xc000
	ds_read_b128 v[198:201], v194
	ds_read_b128 v[202:205], v194 offset:1024
	ds_read_b128 v[206:209], v194 offset:2048
	ds_read_b128 v[210:213], v194 offset:3072
	ds_read_b128 v[214:217], v194 offset:4096
	ds_read_b128 v[218:221], v194 offset:5120
	ds_read_b128 v[226:229], v194 offset:6144
	ds_read_b128 v[230:233], v194 offset:7168
	global_load_lds_dwordx4 v[186:187], off
	v_lshl_add_u64 v[186:187], s[0:1], 0, v[180:181]
	s_add_i32 m0, s95, 0xe000
	s_nop 0
	global_load_lds_dwordx4 v[186:187], off
	s_waitcnt vmcnt(8)
	s_waitcnt lgkmcnt(0)
	s_barrier
	s_setprio 1
	s_waitcnt lgkmcnt(0)
	v_mfma_f32_16x16x32_bf16 v[142:145], v[26:29], v[198:201], 0
	v_mfma_f32_16x16x32_bf16 v[138:141], v[42:45], v[198:201], 0
	v_mfma_f32_16x16x32_bf16 v[126:129], v[26:29], v[206:209], 0
	v_mfma_f32_16x16x32_bf16 v[122:125], v[42:45], v[206:209], 0
	v_mfma_f32_16x16x32_bf16 v[110:113], v[26:29], v[214:217], 0
	v_mfma_f32_16x16x32_bf16 v[106:109], v[42:45], v[214:217], 0
	v_mfma_f32_16x16x32_bf16 v[94:97], v[26:29], v[226:229], 0
	v_mfma_f32_16x16x32_bf16 v[90:93], v[42:45], v[226:229], 0
	v_mfma_f32_16x16x32_bf16 v[142:145], v[30:33], v[202:205], v[142:145]
	v_mfma_f32_16x16x32_bf16 v[138:141], v[46:49], v[202:205], v[138:141]
	v_mfma_f32_16x16x32_bf16 v[126:129], v[30:33], v[210:213], v[126:129]
	v_mfma_f32_16x16x32_bf16 v[122:125], v[46:49], v[210:213], v[122:125]
	v_mfma_f32_16x16x32_bf16 v[110:113], v[30:33], v[218:221], v[110:113]
	v_mfma_f32_16x16x32_bf16 v[106:109], v[46:49], v[218:221], v[106:109]
	v_mfma_f32_16x16x32_bf16 v[94:97], v[30:33], v[230:233], v[94:97]
	v_mfma_f32_16x16x32_bf16 v[90:93], v[46:49], v[230:233], v[90:93]
	s_setprio 0
	s_setprio 1
	v_mfma_f32_16x16x32_bf16 v[134:137], v[146:149], v[198:201], 0
	v_mfma_f32_16x16x32_bf16 v[130:133], v[154:157], v[198:201], 0
	v_mfma_f32_16x16x32_bf16 v[118:121], v[146:149], v[206:209], 0
	v_mfma_f32_16x16x32_bf16 v[114:117], v[154:157], v[206:209], 0
	v_mfma_f32_16x16x32_bf16 v[102:105], v[146:149], v[214:217], 0
	v_mfma_f32_16x16x32_bf16 v[98:101], v[154:157], v[214:217], 0
	v_mfma_f32_16x16x32_bf16 v[86:89], v[146:149], v[226:229], 0
	v_mfma_f32_16x16x32_bf16 v[82:85], v[154:157], v[226:229], 0
	v_mfma_f32_16x16x32_bf16 v[134:137], v[150:153], v[202:205], v[134:137]
	v_mfma_f32_16x16x32_bf16 v[130:133], v[158:161], v[202:205], v[130:133]
	v_mfma_f32_16x16x32_bf16 v[118:121], v[150:153], v[210:213], v[118:121]
	v_mfma_f32_16x16x32_bf16 v[114:117], v[158:161], v[210:213], v[114:117]
	v_mfma_f32_16x16x32_bf16 v[102:105], v[150:153], v[218:221], v[102:105]
	v_mfma_f32_16x16x32_bf16 v[98:101], v[158:161], v[218:221], v[98:101]
	v_mfma_f32_16x16x32_bf16 v[86:89], v[150:153], v[230:233], v[86:89]
	v_mfma_f32_16x16x32_bf16 v[82:85], v[158:161], v[230:233], v[82:85]
	s_setprio 0
	s_barrier
	s_add_i32 s29, s94, s47
	v_lshl_add_u64 v[186:187], s[6:7], 0, v[166:167]
	s_mov_b32 m0, s29
	ds_read_b128 v[198:201], v194 offset:16384
	ds_read_b128 v[202:205], v194 offset:17408
	ds_read_b128 v[206:209], v194 offset:18432
	ds_read_b128 v[210:213], v194 offset:19456
	ds_read_b128 v[214:217], v194 offset:20480
	ds_read_b128 v[218:221], v194 offset:21504
	ds_read_b128 v[226:229], v194 offset:22528
	ds_read_b128 v[230:233], v194 offset:23552
	global_load_lds_dwordx4 v[186:187], off
	s_add_i32 m0, s29, 0x2000
	s_add_u32 s36, s6, 0x40000
	v_lshl_add_u64 v[222:223], s[6:7], 0, v[170:171]
	s_addc_u32 s37, s7, 0
	s_add_i32 s29, s18, s47
	global_load_lds_dwordx4 v[222:223], off
	v_lshl_add_u64 v[234:235], s[36:37], 0, v[166:167]
	s_mov_b32 m0, s29
	v_lshl_add_u64 v[236:237], s[12:13], 0, v[168:169]
	global_load_lds_dwordx4 v[234:235], off
	v_lshl_add_u64 v[234:235], s[36:37], 0, v[170:171]
	s_add_i32 m0, s29, 0x2000
	s_nop 0
	global_load_lds_dwordx4 v[234:235], off
	v_lshl_add_u64 v[234:235], s[12:13], 0, v[164:165]
	s_mov_b32 m0, s95
	s_nop 0
	global_load_lds_dwordx4 v[234:235], off
	s_mov_b32 m0, s96
	s_nop 0
	global_load_lds_dwordx4 v[236:237], off
	s_waitcnt vmcnt(8)
	s_waitcnt lgkmcnt(0)
	s_barrier
	s_setprio 1
	s_waitcnt lgkmcnt(0)
	v_mfma_f32_16x16x32_bf16 v[78:81], v[26:29], v[198:201], 0
	v_mfma_f32_16x16x32_bf16 v[74:77], v[42:45], v[198:201], 0
	v_mfma_f32_16x16x32_bf16 v[62:65], v[26:29], v[206:209], 0
	v_mfma_f32_16x16x32_bf16 v[58:61], v[42:45], v[206:209], 0
	v_mfma_f32_16x16x32_bf16 v[38:41], v[26:29], v[214:217], 0
	v_mfma_f32_16x16x32_bf16 v[34:37], v[42:45], v[214:217], 0
	v_mfma_f32_16x16x32_bf16 v[14:17], v[26:29], v[226:229], 0
	v_mfma_f32_16x16x32_bf16 v[10:13], v[42:45], v[226:229], 0
	v_mfma_f32_16x16x32_bf16 v[78:81], v[30:33], v[202:205], v[78:81]
	v_mfma_f32_16x16x32_bf16 v[74:77], v[46:49], v[202:205], v[74:77]
	v_mfma_f32_16x16x32_bf16 v[62:65], v[30:33], v[210:213], v[62:65]
	v_mfma_f32_16x16x32_bf16 v[58:61], v[46:49], v[210:213], v[58:61]
	v_mfma_f32_16x16x32_bf16 v[38:41], v[30:33], v[218:221], v[38:41]
	v_mfma_f32_16x16x32_bf16 v[34:37], v[46:49], v[218:221], v[34:37]
	v_mfma_f32_16x16x32_bf16 v[14:17], v[30:33], v[230:233], v[14:17]
	v_mfma_f32_16x16x32_bf16 v[10:13], v[46:49], v[230:233], v[10:13]
	s_setprio 0
	s_setprio 1
	v_mfma_f32_16x16x32_bf16 v[22:25], v[146:149], v[214:217], 0
	v_mfma_f32_16x16x32_bf16 v[18:21], v[154:157], v[214:217], 0
	v_mfma_f32_16x16x32_bf16 v[6:9], v[146:149], v[226:229], 0
	v_mfma_f32_16x16x32_bf16 v[2:5], v[154:157], v[226:229], 0
	v_mfma_f32_16x16x32_bf16 v[26:29], v[146:149], v[198:201], 0
	v_mfma_f32_16x16x32_bf16 v[30:33], v[154:157], v[198:201], 0
	v_mfma_f32_16x16x32_bf16 v[42:45], v[146:149], v[206:209], 0
	v_mfma_f32_16x16x32_bf16 v[46:49], v[154:157], v[206:209], 0
	v_mfma_f32_16x16x32_bf16 v[22:25], v[150:153], v[218:221], v[22:25]
	v_mfma_f32_16x16x32_bf16 v[18:21], v[158:161], v[218:221], v[18:21]
	v_mfma_f32_16x16x32_bf16 v[6:9], v[150:153], v[230:233], v[6:9]
	v_mfma_f32_16x16x32_bf16 v[2:5], v[158:161], v[230:233], v[2:5]
	v_mfma_f32_16x16x32_bf16 v[26:29], v[150:153], v[202:205], v[26:29]
	v_mfma_f32_16x16x32_bf16 v[30:33], v[158:161], v[202:205], v[30:33]
	v_mfma_f32_16x16x32_bf16 v[42:45], v[150:153], v[210:213], v[42:45]
	v_mfma_f32_16x16x32_bf16 v[46:49], v[158:161], v[210:213], v[46:49]
	s_setprio 0
	s_barrier
	s_branch .Lmid_P1

; template <class Epi, int AC0, int BC0, int NT0, int AC1, int BC1, int NT1>
; __device__ __forceinline__ void gemm_phase(LAS unsigned char* lds, const Gemm g, const StaticOrder& S, const Epi& E, int tid) {
;     ...
;         const char* nA = has_next ? PG8_APTR(nxt) : cA; const char* nB = has_next ? PG8_BPTR(nxt) : cB;
;         const int nt = NT0 + cur.seg * (NT1 - NT0);
;         for (int t = 0; t < nt; t += 2) {
;             const bool last = (t == nt - 2);
;             const char* a1 = cA + (size_t)(t + 1) * kstep;
;             const char* a2 = last ? nA : cA + (size_t)(t + 2) * kstep; const char* b2 = last ? nB : cB + (size_t)(t + 2) * kstep;
;             const char* a3 = a2 + kstep; const char* b3 = b2 + kstep;
;     ...
;             for (int a = 0; a < 2; ++a)
; #pragma unroll
;                 for (int b = 0; b < 2; ++b)
; #pragma unroll
;                     for (int m = 0; m < 4; ++m)
; #pragma unroll
;                         for (int n = 0; n < 2; ++n) acc[a][b][m][n] = (f32x4){0.f, 0.f, 0.f, 0.f};
.LBB0_123:
	s_ashr_i32 s29, s28, 31
	s_lshl_b64 s[12:13], s[28:29], 19
	s_add_u32 s30, s80, s12
	s_addc_u32 s31, s81, s13
	s_and_b64 s[12:13], s[4:5], exec
	s_cselect_b32 s3, s31, s1
	s_cselect_b32 s9, s30, s0
	s_ashr_i32 s27, s26, 31
	s_lshl_b64 s[12:13], s[26:27], 19
	v_readlane_b32 s34, v254, 4
	v_readlane_b32 s35, v254, 5
	s_add_u32 s34, s34, s12
	s_addc_u32 s35, s35, s13
	s_and_b64 s[12:13], s[4:5], exec
	s_cselect_b32 s11, s35, s7
	s_cselect_b32 s15, s34, s6
	s_add_u32 s0, s0, 0x40080
	s_addc_u32 s1, s1, 0
	s_add_u32 s16, s6, 0x100
	s_addc_u32 s22, s7, 0
	s_mov_b32 s27, -2
	s_cmp_lg_u32 s14, 1
	s_cbranch_scc1 .Lpeel_P1
	v_mov_b32_e32 v2, 0
	v_mov_b32_e32 v3, v2
	v_mov_b32_e32 v4, v2
	v_mov_b32_e32 v5, v2
	v_mov_b32_e32 v6, v2
	v_mov_b32_e32 v7, v2
	v_mov_b32_e32 v8, v2
	v_mov_b32_e32 v9, v2
	v_mov_b32_e32 v18, v2
	v_mov_b32_e32 v19, v2
	v_mov_b32_e32 v20, v2
	v_mov_b32_e32 v21, v2
	v_mov_b32_e32 v22, v2
	v_mov_b32_e32 v23, v2
	v_mov_b32_e32 v24, v2
	v_mov_b32_e32 v25, v2
	v_mov_b32_e32 v50, v2
	v_mov_b32_e32 v51, v2
	v_mov_b32_e32 v52, v2
	v_mov_b32_e32 v53, v2
	v_mov_b32_e32 v54, v2
	v_mov_b32_e32 v55, v2
	v_mov_b32_e32 v56, v2
	v_mov_b32_e32 v57, v2
	v_mov_b32_e32 v66, v2
	v_mov_b32_e32 v67, v2
	v_mov_b32_e32 v68, v2
	v_mov_b32_e32 v69, v2
	v_mov_b32_e32 v70, v2
	v_mov_b32_e32 v71, v2
	v_mov_b32_e32 v72, v2
	v_mov_b32_e32 v73, v2
	v_mov_b32_e32 v10, v2
	v_mov_b32_e32 v11, v2
	v_mov_b32_e32 v12, v2
	v_mov_b32_e32 v13, v2
	v_mov_b32_e32 v14, v2
	v_mov_b32_e32 v15, v2
	v_mov_b32_e32 v16, v2
	v_mov_b32_e32 v17, v2
	v_mov_b32_e32 v34, v2
	v_mov_b32_e32 v35, v2
	v_mov_b32_e32 v36, v2
	v_mov_b32_e32 v37, v2
	v_mov_b32_e32 v38, v2
	v_mov_b32_e32 v39, v2
	v_mov_b32_e32 v40, v2
	v_mov_b32_e32 v41, v2
	v_mov_b32_e32 v58, v2
	v_mov_b32_e32 v59, v2
	v_mov_b32_e32 v60, v2
	v_mov_b32_e32 v61, v2
	v_mov_b32_e32 v62, v2
	v_mov_b32_e32 v63, v2
	v_mov_b32_e32 v64, v2
	v_mov_b32_e32 v65, v2
	v_mov_b32_e32 v74, v2
	v_mov_b32_e32 v75, v2
	v_mov_b32_e32 v76, v2
	v_mov_b32_e32 v77, v2
	v_mov_b32_e32 v78, v2
	v_mov_b32_e32 v79, v2
	v_mov_b32_e32 v80, v2
	v_mov_b32_e32 v81, v2
	v_mov_b32_e32 v82, v2
	v_mov_b32_e32 v83, v2
	v_mov_b32_e32 v84, v2
	v_mov_b32_e32 v85, v2
	v_mov_b32_e32 v86, v2
	v_mov_b32_e32 v87, v2
	v_mov_b32_e32 v88, v2
	v_mov_b32_e32 v89, v2
	v_mov_b32_e32 v98, v2
	v_mov_b32_e32 v99, v2
	v_mov_b32_e32 v100, v2
	v_mov_b32_e32 v101, v2
	v_mov_b32_e32 v102, v2
	v_mov_b32_e32 v103, v2
	v_mov_b32_e32 v104, v2
	v_mov_b32_e32 v105, v2
	v_mov_b32_e32 v114, v2
	v_mov_b32_e32 v115, v2
	v_mov_b32_e32 v116, v2
	v_mov_b32_e32 v117, v2
	v_mov_b32_e32 v118, v2
	v_mov_b32_e32 v119, v2
	v_mov_b32_e32 v120, v2
	v_mov_b32_e32 v121, v2
	v_mov_b32_e32 v130, v2
	v_mov_b32_e32 v131, v2
	v_mov_b32_e32 v132, v2
	v_mov_b32_e32 v133, v2
	v_mov_b32_e32 v134, v2
	v_mov_b32_e32 v135, v2
	v_mov_b32_e32 v136, v2
	v_mov_b32_e32 v137, v2
	v_mov_b32_e32 v90, v2
	v_mov_b32_e32 v91, v2
	v_mov_b32_e32 v92, v2
	v_mov_b32_e32 v93, v2
	v_mov_b32_e32 v94, v2
	v_mov_b32_e32 v95, v2
	v_mov_b32_e32 v96, v2
	v_mov_b32_e32 v97, v2
	v_mov_b32_e32 v106, v2
	v_mov_b32_e32 v107, v2
	v_mov_b32_e32 v108, v2
	v_mov_b32_e32 v109, v2
	v_mov_b32_e32 v110, v2
	v_mov_b32_e32 v111, v2
	v_mov_b32_e32 v112, v2
	v_mov_b32_e32 v113, v2
	v_mov_b32_e32 v122, v2
	v_mov_b32_e32 v123, v2
	v_mov_b32_e32 v124, v2
	v_mov_b32_e32 v125, v2
	v_mov_b32_e32 v126, v2
	v_mov_b32_e32 v127, v2
	v_mov_b32_e32 v128, v2
	v_mov_b32_e32 v129, v2
	v_mov_b32_e32 v138, v2
	v_mov_b32_e32 v139, v2
	v_mov_b32_e32 v140, v2
	v_mov_b32_e32 v141, v2
	v_mov_b32_e32 v142, v2
	v_mov_b32_e32 v143, v2
	v_mov_b32_e32 v144, v2
	v_mov_b32_e32 v145, v2

; template <bool WIN>
; __device__ __forceinline__ void attn_item(bf16_t* U, const float* sink, int ci, int h, LAS unsigned char* wl, const LAS float* tbl, int lane_in) {
;     ...
;                 if (s < 12) {
; #pragma unroll
;                     for (int r = 0; r < 16; ++r) C0[r] = 0.f;
;                 } else {
;                     const int base = 512 + iq - 32 * s - 4 * hi + 128;
; #pragma unroll
;                     for (int r = 0; r < 16; ++r) { const int cr = (r & 3) + 8 * (r >> 2); int i0 = base - cr; i0 = i0 > 256 ? 256 : i0; C0[r] = th[i0]; }
;                 }
.LBB0_620:
	s_cmp_lt_u32 s21, 12
	s_cbranch_scc1 .Lzqk
	s_cmp_gt_u32 s21, 11
	v_mov_b32_e32 v66, 0
	s_cselect_b64 s[6:7], -1, 0
	s_cmp_lt_u32 s21, 12
	v_add_u32_e32 v130, s36, v207
	v_mov_b32_e32 v82, 0
	v_mov_b32_e32 v83, 0
	v_mov_b32_e32 v84, 0
	v_mov_b32_e32 v85, 0
	v_mov_b32_e32 v86, 0
	v_mov_b32_e32 v87, 0
	v_mov_b32_e32 v88, 0
	v_mov_b32_e32 v89, 0
	v_mov_b32_e32 v90, 0
	v_mov_b32_e32 v91, 0
	v_mov_b32_e32 v92, 0
	v_mov_b32_e32 v93, 0
	v_mov_b32_e32 v94, 0
	v_mov_b32_e32 v95, 0
	v_mov_b32_e32 v96, 0
	v_mov_b32_e32 v97, 0
	s_cbranch_scc1 .LBB0_622
	v_add_u32_e32 v67, 0x280, v130
	v_min_i32_e32 v67, 0x100, v67
	v_add_u32_e32 v68, 0x27f, v130
	v_add_u32_e32 v69, 0x27e, v130
	v_add_u32_e32 v70, 0x27d, v130
	v_add_u32_e32 v71, 0x278, v130
	v_add_u32_e32 v72, 0x277, v130
	v_add_u32_e32 v73, 0x276, v130
	v_add_u32_e32 v74, 0x275, v130
	v_lshl_add_u32 v67, v67, 2, s17
	v_min_i32_e32 v68, 0x100, v68
	v_min_i32_e32 v69, 0x100, v69
	v_min_i32_e32 v70, 0x100, v70
	v_min_i32_e32 v71, 0x100, v71
	v_min_i32_e32 v72, 0x100, v72
	v_min_i32_e32 v73, 0x100, v73
	v_min_i32_e32 v74, 0x100, v74
	v_lshl_add_u32 v68, v68, 2, s17
	v_lshl_add_u32 v69, v69, 2, s17
	v_lshl_add_u32 v70, v70, 2, s17
	v_lshl_add_u32 v71, v71, 2, s17
	v_lshl_add_u32 v72, v72, 2, s17
	v_lshl_add_u32 v73, v73, 2, s17
	v_lshl_add_u32 v74, v74, 2, s17
	ds_read_b32 v82, v67
	ds_read_b32 v83, v68
	ds_read_b32 v84, v69
	ds_read_b32 v85, v70
	ds_read_b32 v86, v71
	ds_read_b32 v87, v72
	ds_read_b32 v88, v73
	ds_read_b32 v89, v74
	v_add_u32_e32 v67, 0x270, v130
	v_min_i32_e32 v67, 0x100, v67
	v_add_u32_e32 v68, 0x26f, v130
	v_add_u32_e32 v69, 0x26e, v130
	v_add_u32_e32 v70, 0x26d, v130
	v_add_u32_e32 v71, 0x268, v130
	v_add_u32_e32 v72, 0x267, v130
	v_add_u32_e32 v73, 0x266, v130
	v_add_u32_e32 v74, 0x265, v130
	v_lshl_add_u32 v67, v67, 2, s17
	v_min_i32_e32 v68, 0x100, v68
	v_min_i32_e32 v69, 0x100, v69
	v_min_i32_e32 v70, 0x100, v70
	v_min_i32_e32 v71, 0x100, v71
	v_min_i32_e32 v72, 0x100, v72
	v_min_i32_e32 v73, 0x100, v73
	v_min_i32_e32 v74, 0x100, v74
	v_lshl_add_u32 v68, v68, 2, s17
	v_lshl_add_u32 v69, v69, 2, s17
	v_lshl_add_u32 v70, v70, 2, s17
	v_lshl_add_u32 v71, v71, 2, s17
	v_lshl_add_u32 v72, v72, 2, s17
	v_lshl_add_u32 v73, v73, 2, s17
	v_lshl_add_u32 v74, v74, 2, s17
	ds_read_b32 v90, v67
	ds_read_b32 v91, v68
	ds_read_b32 v92, v69
	ds_read_b32 v93, v70
	ds_read_b32 v94, v71
	ds_read_b32 v95, v72
	ds_read_b32 v96, v73
	ds_read_b32 v97, v74

; template <bool WIN>
; __device__ __forceinline__ void attn_item(bf16_t* U, const float* sink, int ci, int h, LAS unsigned char* wl, const LAS float* tbl, int lane_in) {
;     ...
;         { s16x4 tl[4], tu[4];
;             const unsigned va = (unsigned)(uintptr_t)(wb + vfo);
;             asm volatile("ds_read_b64_tr_b16 %0, %8\n\tds_read_b64_tr_b16 %1, %8 offset:512\n\tds_read_b64_tr_b16 %2, %8 offset:1024\n\tds_read_b64_tr_b16 %3, %8 offset:1536\n\t"
;                          "ds_read_b64_tr_b16 %4, %8 offset:2048\n\tds_read_b64_tr_b16 %5, %8 offset:2560\n\tds_read_b64_tr_b16 %6, %8 offset:3072\n\tds_read_b64_tr_b16 %7, %8 offset:3584\n\t"
;                          "s_waitcnt lgkmcnt(0)"
;                          : "=&v"(tl[0]), "=&v"(tu[0]), "=&v"(tl[1]), "=&v"(tu[1]), "=&v"(tl[2]), "=&v"(tu[2]), "=&v"(tl[3]), "=&v"(tu[3]) : "v"(va) : "memory");
; #pragma unroll
;             for (int i = 0; i < 4; ++i) vf[i >> 1][i & 1] = (bf16x8){tl[i][0], tl[i][1], tl[i][2], tl[i][3], tu[i][0], tu[i][1], tu[i][2], tu[i][3]}; }
;         if (s + 2 < NS) ATT_DMA(s + 2);
.Lafter_qk:
	v_add3_u32 v130, s6, v205, v1
	v_add3_u32 v208, v130, v206, s20
	ds_read_b64_tr_b16 v[142:143], v208
	ds_read_b64_tr_b16 v[144:145], v208 offset:512
	ds_read_b64_tr_b16 v[138:139], v208 offset:1024
	ds_read_b64_tr_b16 v[140:141], v208 offset:1536
	ds_read_b64_tr_b16 v[134:135], v208 offset:2048
	ds_read_b64_tr_b16 v[136:137], v208 offset:2560
	ds_read_b64_tr_b16 v[130:131], v208 offset:3072
	ds_read_b64_tr_b16 v[132:133], v208 offset:3584
	s_waitcnt lgkmcnt(0)
	s_cmp_gt_u32 s21, 15
	s_cbranch_scc1 .LBB0_615
	s_cmp_lt_u32 s21, 14
	s_cselect_b64 s[6:7], -1, 0
	s_and_b64 s[6:7], s[4:5], s[6:7]
	s_and_b32 s38, s11, 0x3c0
	s_and_b64 s[6:7], s[6:7], exec
	s_cselect_b32 s6, s33, s10
	s_and_b32 s39, s21, 1
	s_lshl_b32 s7, s39, 5
	s_or_b32 s7, s38, s7
	s_add_i32 s6, s7, s6
	s_mul_hi_i32 s7, s6, 0x2a00
	s_mulk_i32 s6, 0x2a00
	s_add_u32 s6, s82, s6
	s_addc_u32 s7, s83, s7
	s_lshl_b32 s38, s39, 13
	s_add_i32 s38, s22, s38
	s_mov_b64 s[40:41], s[6:7]
	s_mov_b32 s42, s38
	s_branch .L615d

; #define LAS __attribute__((address_space(3)))
; template <bool WIN>
; __device__ __forceinline__ void attn_item(bf16_t* U, const float* sink, int ci, int h, LAS unsigned char* wl, const LAS float* tbl, int lane_in) {
;     ...
;         {
;             bf16x8 kf[4];
; #pragma unroll
;             for (int d0 = 0; d0 < 4; ++d0) kf[d0] = *(const LAS bf16x8*)(wb + kfo[d0]);
;             asm volatile("s_waitcnt lgkmcnt(0)" ::: "memory");
;             __builtin_amdgcn_sched_barrier(0);
; #pragma unroll
;             for (int d0 = 0; d0 < 4; ++d0) {
;                 Cq[0] = __builtin_amdgcn_mfma_f32_32x32x16_bf16(kf[d0], qr[0][d0], Cq[0], 0, 0, 0);
;                 Cq[1] = __builtin_amdgcn_mfma_f32_32x32x16_bf16(kf[d0], qr[1][d0], Cq[1], 0, 0, 0);
;             }
;         }
.Lzqk:
	s_and_b32 s6, s37, 0x2000
	s_add_i32 s6, s22, s6
	v_add3_u32 v130, s6, v201, v200
	v_add3_u32 v134, s6, v202, v200
	v_add3_u32 v138, s6, v203, v200
	v_add3_u32 v142, s6, v204, v200
	ds_read_b128 v[130:133], v130
	ds_read_b128 v[134:137], v134
	ds_read_b128 v[138:141], v138
	ds_read_b128 v[142:145], v142
	s_waitcnt lgkmcnt(0)
	s_waitcnt lgkmcnt(0)
	v_mfma_f32_32x32x16_bf16 v[82:97], v[130:133], v[98:101], 0
	v_mfma_f32_32x32x16_bf16 v[66:81], v[130:133], v[114:117], 0
	v_mfma_f32_32x32x16_bf16 v[82:97], v[134:137], v[102:105], v[82:97]
	v_mfma_f32_32x32x16_bf16 v[66:81], v[134:137], v[118:121], v[66:81]
	v_mfma_f32_32x32x16_bf16 v[82:97], v[138:141], v[106:109], v[82:97]
	v_mfma_f32_32x32x16_bf16 v[66:81], v[138:141], v[122:125], v[66:81]
	v_mfma_f32_32x32x16_bf16 v[82:97], v[142:145], v[110:113], v[82:97]
	v_mfma_f32_32x32x16_bf16 v[66:81], v[142:145], v[126:129], v[66:81]
	s_branch .Lafter_qk

; #define PG8_STAGE(bufoff, gbase, voff) do { _Pragma("unroll") for (int _i = 0; _i < 2; ++_i) \
;         __builtin_amdgcn_global_load_lds((const unsigned*)((const char*)(gbase) + (voff)[_i]), (LAS unsigned*)(lds + (bufoff) + ldsw + _i * 8192), 16, 0, 0); } while (0)
; #define PG8_LDA(dst, b, h) do { _Pragma("unroll") for (int m = 0; m < 4; ++m) _Pragma("unroll") for (int k = 0; k < 2; ++k) dst[m][k] = *(const LAS bf16x8*)(lds + PG8_SA(b, h) + aoff + m * 2048 + k * 1024); } while (0)
; #define PG8_LDB(dst, b, h) do { _Pragma("unroll") for (int n = 0; n < 2; ++n) _Pragma("unroll") for (int k = 0; k < 2; ++k) dst[n][k] = *(const LAS bf16x8*)(lds + PG8_SB(b, h) + boff + n * 2048 + k * 1024); } while (0)
; #define PG8_MMA(ai, bj, At, Bt) do { __builtin_amdgcn_s_setprio(1); _Pragma("unroll") for (int m = 0; m < 4; ++m) _Pragma("unroll") for (int n = 0; n < 2; ++n) _Pragma("unroll") for (int k = 0; k < 2; ++k) \
;         acc[ai][bj][m][n] = __builtin_amdgcn_mfma_f32_16x16x32_bf16(Bt[n][k], At[m][k], acc[ai][bj][m][n], 0, 0, 0); __builtin_amdgcn_s_setprio(0); } while (0)
; #define PG8_WAIT_V(n) asm volatile("s_waitcnt vmcnt(" #n ")" ::: "memory")
; #define PG8_WAIT_L(n) asm volatile("s_waitcnt lgkmcnt(" #n ")" ::: "memory")
; #define PG8_BAR __builtin_amdgcn_s_barrier()
; template <class Epi, int AC0, int BC0, int NT0, int AC1, int BC1, int NT1>
; __device__ __forceinline__ void gemm_phase(LAS unsigned char* lds, const Gemm g, const StaticOrder& S, const Epi& E, int tid) {
;     ...
;         for (int t = 0; t < nt; t += 2) {
;             const bool last = (t == nt - 2);
;             const char* a1 = cA + (size_t)(t + 1) * kstep;
;             const char* a2 = last ? nA : cA + (size_t)(t + 2) * kstep; const char* b2 = last ? nB : cB + (size_t)(t + 2) * kstep;
;             const char* a3 = a2 + kstep; const char* b3 = b2 + kstep;
;             PG8_LDB(B0, 0, 0); PG8_LDB(B1, 0, 1); PG8_SCHED; PG8_LDA(At, 0, 0); PG8_STAGE(PG8_SA(1, 1), a1 + hstepA, voffA);
;             PG8_WAIT_V(8); PG8_WAIT_L(0); PG8_BAR; PG8_MMA(0, 0, At, B0); PG8_MMA(0, 1, At, B1); PG8_BAR; PG8_SCHED;
;             PG8_LDA(At, 0, 1); PG8_STAGE(PG8_SB(0, 0), b2, voffB); PG8_STAGE(PG8_SB(0, 1), b2 + hstepB, voffB); PG8_STAGE(PG8_SA(0, 0), a2, voffA);
;             PG8_WAIT_V(8); PG8_WAIT_L(0); PG8_BAR; PG8_MMA(1, 0, At, B0); PG8_MMA(1, 1, At, B1); PG8_BAR; PG8_SCHED;
.Lpeel_P4:
	ds_read_b128 v[130:133], v218
	ds_read_b128 v[134:137], v218 offset:1024
	ds_read_b128 v[138:141], v218 offset:2048
	ds_read_b128 v[142:145], v218 offset:3072
	ds_read_b128 v[146:149], v219
	ds_read_b128 v[150:153], v219 offset:1024
	ds_read_b128 v[154:157], v219 offset:2048
	ds_read_b128 v[158:161], v219 offset:3072
	s_add_u32 s20, s18, 0xfffc0080
	s_addc_u32 s21, s19, -1
	s_cmp_eq_u32 s73, 12
	s_cselect_b32 s67, s0, s21
	s_cselect_b32 s66, s2, s20
	s_cselect_b32 s21, s3, s33
	s_cselect_b32 s20, s13, s15
	v_lshl_add_u64 v[212:213], s[18:19], 0, v[198:199]
	s_add_i32 m0, s26, 0xc000
	ds_read_b128 v[162:165], v220
	ds_read_b128 v[166:169], v220 offset:1024
	ds_read_b128 v[170:173], v220 offset:2048
	ds_read_b128 v[174:177], v220 offset:3072
	ds_read_b128 v[178:181], v220 offset:4096
	ds_read_b128 v[182:185], v220 offset:5120
	ds_read_b128 v[204:207], v220 offset:6144
	ds_read_b128 v[208:211], v220 offset:7168
	global_load_lds_dwordx4 v[212:213], off
	v_lshl_add_u64 v[212:213], s[18:19], 0, v[200:201]
	s_add_i32 m0, s26, 0xe000
	s_nop 0
	global_load_lds_dwordx4 v[212:213], off
	s_waitcnt vmcnt(8)
	s_waitcnt lgkmcnt(0)
	s_barrier
	s_setprio 1
	s_waitcnt lgkmcnt(0)
	v_mfma_f32_16x16x32_bf16 v[126:129], v[130:133], v[162:165], 0
	v_mfma_f32_16x16x32_bf16 v[122:125], v[138:141], v[162:165], 0
	v_mfma_f32_16x16x32_bf16 v[110:113], v[130:133], v[170:173], 0
	v_mfma_f32_16x16x32_bf16 v[106:109], v[138:141], v[170:173], 0
	v_mfma_f32_16x16x32_bf16 v[94:97], v[130:133], v[178:181], 0
	v_mfma_f32_16x16x32_bf16 v[90:93], v[138:141], v[178:181], 0
	v_mfma_f32_16x16x32_bf16 v[78:81], v[130:133], v[204:207], 0
	v_mfma_f32_16x16x32_bf16 v[74:77], v[138:141], v[204:207], 0
	v_mfma_f32_16x16x32_bf16 v[126:129], v[134:137], v[166:169], v[126:129]
	v_mfma_f32_16x16x32_bf16 v[122:125], v[142:145], v[166:169], v[122:125]
	v_mfma_f32_16x16x32_bf16 v[110:113], v[134:137], v[174:177], v[110:113]
	v_mfma_f32_16x16x32_bf16 v[106:109], v[142:145], v[174:177], v[106:109]
	v_mfma_f32_16x16x32_bf16 v[94:97], v[134:137], v[182:185], v[94:97]
	v_mfma_f32_16x16x32_bf16 v[90:93], v[142:145], v[182:185], v[90:93]
	v_mfma_f32_16x16x32_bf16 v[78:81], v[134:137], v[208:211], v[78:81]
	v_mfma_f32_16x16x32_bf16 v[74:77], v[142:145], v[208:211], v[74:77]
	s_setprio 0
	s_setprio 1
	v_mfma_f32_16x16x32_bf16 v[118:121], v[146:149], v[162:165], 0
	v_mfma_f32_16x16x32_bf16 v[114:117], v[154:157], v[162:165], 0
	v_mfma_f32_16x16x32_bf16 v[102:105], v[146:149], v[170:173], 0
	v_mfma_f32_16x16x32_bf16 v[98:101], v[154:157], v[170:173], 0
	v_mfma_f32_16x16x32_bf16 v[86:89], v[146:149], v[178:181], 0
	v_mfma_f32_16x16x32_bf16 v[82:85], v[154:157], v[178:181], 0
	v_mfma_f32_16x16x32_bf16 v[70:73], v[146:149], v[204:207], 0
	v_mfma_f32_16x16x32_bf16 v[66:69], v[154:157], v[204:207], 0
	v_mfma_f32_16x16x32_bf16 v[118:121], v[150:153], v[166:169], v[118:121]
	v_mfma_f32_16x16x32_bf16 v[114:117], v[158:161], v[166:169], v[114:117]
	v_mfma_f32_16x16x32_bf16 v[102:105], v[150:153], v[174:177], v[102:105]
	v_mfma_f32_16x16x32_bf16 v[98:101], v[158:161], v[174:177], v[98:101]
	v_mfma_f32_16x16x32_bf16 v[86:89], v[150:153], v[182:185], v[86:89]
	v_mfma_f32_16x16x32_bf16 v[82:85], v[158:161], v[182:185], v[82:85]
	v_mfma_f32_16x16x32_bf16 v[70:73], v[150:153], v[208:211], v[70:73]
	v_mfma_f32_16x16x32_bf16 v[66:69], v[158:161], v[208:211], v[66:69]
	s_setprio 0
	s_barrier
	s_add_i32 s75, s52, s25
	v_lshl_add_u64 v[212:213], s[20:21], 0, v[188:189]
	s_mov_b32 m0, s75
	ds_read_b128 v[162:165], v220 offset:16384
	ds_read_b128 v[166:169], v220 offset:17408
	ds_read_b128 v[170:173], v220 offset:18432
	ds_read_b128 v[174:177], v220 offset:19456
	ds_read_b128 v[178:181], v220 offset:20480
	ds_read_b128 v[182:185], v220 offset:21504
	ds_read_b128 v[204:207], v220 offset:22528
	ds_read_b128 v[208:211], v220 offset:23552
	global_load_lds_dwordx4 v[212:213], off
	s_add_i32 m0, s75, 0x2000
	s_add_u32 s76, s20, 0x40000
	v_lshl_add_u64 v[214:215], s[20:21], 0, v[192:193]
	s_addc_u32 s77, s21, 0
	s_add_i32 s75, s53, s25
	global_load_lds_dwordx4 v[214:215], off
	v_lshl_add_u64 v[222:223], s[76:77], 0, v[188:189]
	s_mov_b32 m0, s75
	v_lshl_add_u64 v[224:225], s[66:67], 0, v[190:191]
	global_load_lds_dwordx4 v[222:223], off
	v_lshl_add_u64 v[222:223], s[76:77], 0, v[192:193]
	s_add_i32 m0, s75, 0x2000
	s_nop 0
	global_load_lds_dwordx4 v[222:223], off
	v_lshl_add_u64 v[222:223], s[66:67], 0, v[186:187]
	s_mov_b32 m0, s26
	s_nop 0
	global_load_lds_dwordx4 v[222:223], off
	s_mov_b32 m0, s27
	s_nop 0
	global_load_lds_dwordx4 v[224:225], off
	s_waitcnt vmcnt(8)
	s_waitcnt lgkmcnt(0)
	s_barrier
	s_setprio 1
	s_waitcnt lgkmcnt(0)
	v_mfma_f32_16x16x32_bf16 v[62:65], v[130:133], v[162:165], 0
	v_mfma_f32_16x16x32_bf16 v[58:61], v[138:141], v[162:165], 0
	v_mfma_f32_16x16x32_bf16 v[46:49], v[130:133], v[170:173], 0
	v_mfma_f32_16x16x32_bf16 v[42:45], v[138:141], v[170:173], 0
	v_mfma_f32_16x16x32_bf16 v[30:33], v[130:133], v[178:181], 0
	v_mfma_f32_16x16x32_bf16 v[26:29], v[138:141], v[178:181], 0
	v_mfma_f32_16x16x32_bf16 v[14:17], v[130:133], v[204:207], 0
	v_mfma_f32_16x16x32_bf16 v[10:13], v[138:141], v[204:207], 0
	v_mfma_f32_16x16x32_bf16 v[62:65], v[134:137], v[166:169], v[62:65]
	v_mfma_f32_16x16x32_bf16 v[58:61], v[142:145], v[166:169], v[58:61]
	v_mfma_f32_16x16x32_bf16 v[46:49], v[134:137], v[174:177], v[46:49]
	v_mfma_f32_16x16x32_bf16 v[42:45], v[142:145], v[174:177], v[42:45]
	v_mfma_f32_16x16x32_bf16 v[30:33], v[134:137], v[182:185], v[30:33]
	v_mfma_f32_16x16x32_bf16 v[26:29], v[142:145], v[182:185], v[26:29]
	v_mfma_f32_16x16x32_bf16 v[14:17], v[134:137], v[208:211], v[14:17]
	v_mfma_f32_16x16x32_bf16 v[10:13], v[142:145], v[208:211], v[10:13]
	s_setprio 0
	s_setprio 1
	v_mfma_f32_16x16x32_bf16 v[54:57], v[146:149], v[162:165], 0
	v_mfma_f32_16x16x32_bf16 v[50:53], v[154:157], v[162:165], 0
	v_mfma_f32_16x16x32_bf16 v[38:41], v[146:149], v[170:173], 0
	v_mfma_f32_16x16x32_bf16 v[34:37], v[154:157], v[170:173], 0
	v_mfma_f32_16x16x32_bf16 v[22:25], v[146:149], v[178:181], 0
	v_mfma_f32_16x16x32_bf16 v[18:21], v[154:157], v[178:181], 0
	v_mfma_f32_16x16x32_bf16 v[6:9], v[146:149], v[204:207], 0
	v_mfma_f32_16x16x32_bf16 v[2:5], v[154:157], v[204:207], 0
	v_mfma_f32_16x16x32_bf16 v[54:57], v[150:153], v[166:169], v[54:57]
	v_mfma_f32_16x16x32_bf16 v[50:53], v[158:161], v[166:169], v[50:53]
	v_mfma_f32_16x16x32_bf16 v[38:41], v[150:153], v[174:177], v[38:41]
	v_mfma_f32_16x16x32_bf16 v[34:37], v[158:161], v[174:177], v[34:37]
	v_mfma_f32_16x16x32_bf16 v[22:25], v[150:153], v[182:185], v[22:25]
	v_mfma_f32_16x16x32_bf16 v[18:21], v[158:161], v[182:185], v[18:21]
	v_mfma_f32_16x16x32_bf16 v[6:9], v[150:153], v[208:211], v[6:9]
	v_mfma_f32_16x16x32_bf16 v[2:5], v[158:161], v[208:211], v[2:5]
	s_setprio 0
	s_barrier
	s_branch .Lmid_P4

; template <class Epi, int AC0, int BC0, int NT0, int AC1, int BC1, int NT1>
; __device__ __forceinline__ void gemm_phase(LAS unsigned char* lds, const Gemm g, const StaticOrder& S, const Epi& E, int tid) {
;     ...
;         const char* nA = has_next ? PG8_APTR(nxt) : cA; const char* nB = has_next ? PG8_BPTR(nxt) : cB;
;         const int nt = NT0 + cur.seg * (NT1 - NT0);
;         for (int t = 0; t < nt; t += 2) {
;             const bool last = (t == nt - 2);
;             const char* a1 = cA + (size_t)(t + 1) * kstep;
;             const char* a2 = last ? nA : cA + (size_t)(t + 2) * kstep; const char* b2 = last ? nB : cB + (size_t)(t + 2) * kstep;
;             const char* a3 = a2 + kstep; const char* b3 = b2 + kstep;
;     ...
;             for (int a = 0; a < 2; ++a)
; #pragma unroll
;                 for (int b = 0; b < 2; ++b)
; #pragma unroll
;                     for (int m = 0; m < 4; ++m)
; #pragma unroll
;                         for (int n = 0; n < 2; ++n) acc[a][b][m][n] = (f32x4){0.f, 0.f, 0.f, 0.f};
.LBB0_898:
	s_ashr_i32 s15, s14, 31
	s_lshl_b64 s[2:3], s[14:15], 19
	s_add_u32 s16, s80, s2
	s_addc_u32 s17, s81, s3
	s_and_b64 s[2:3], s[42:43], exec
	s_cselect_b32 s0, s17, s19
	s_cselect_b32 s2, s16, s18
	s_ashr_i32 s13, s12, 31
	s_lshl_b64 s[44:45], s[12:13], 19
	s_add_u32 s44, s96, s44
	s_addc_u32 s45, s97, s45
	s_and_b64 s[66:67], s[42:43], exec
	s_cselect_b32 s3, s45, s21
	s_cselect_b32 s13, s44, s20
	s_add_u32 s18, s18, 0x40080
	s_addc_u32 s19, s19, 0
	s_add_u32 s15, s20, 0x100
	s_addc_u32 s33, s21, 0
	s_mov_b32 s73, -2
	s_waitcnt lgkmcnt(0)
	s_cmp_lg_u32 s55, 1
	s_cbranch_scc1 .Lpeel_P4
	v_mov_b32_e32 v2, 0
	v_mov_b32_e32 v3, v2
	v_mov_b32_e32 v4, v2
	v_mov_b32_e32 v5, v2
	v_mov_b32_e32 v6, v2
	v_mov_b32_e32 v7, v2
	v_mov_b32_e32 v8, v2
	v_mov_b32_e32 v9, v2
	v_mov_b32_e32 v18, v2
	v_mov_b32_e32 v19, v2
	v_mov_b32_e32 v20, v2
	v_mov_b32_e32 v21, v2
	v_mov_b32_e32 v22, v2
	v_mov_b32_e32 v23, v2
	v_mov_b32_e32 v24, v2
	v_mov_b32_e32 v25, v2
	v_mov_b32_e32 v34, v2
	v_mov_b32_e32 v35, v2
	v_mov_b32_e32 v36, v2
	v_mov_b32_e32 v37, v2
	v_mov_b32_e32 v38, v2
	v_mov_b32_e32 v39, v2
	v_mov_b32_e32 v40, v2
	v_mov_b32_e32 v41, v2
	v_mov_b32_e32 v50, v2
	v_mov_b32_e32 v51, v2
	v_mov_b32_e32 v52, v2
	v_mov_b32_e32 v53, v2
	v_mov_b32_e32 v54, v2
	v_mov_b32_e32 v55, v2
	v_mov_b32_e32 v56, v2
	v_mov_b32_e32 v57, v2
	v_mov_b32_e32 v10, v2
	v_mov_b32_e32 v11, v2
	v_mov_b32_e32 v12, v2
	v_mov_b32_e32 v13, v2
	v_mov_b32_e32 v14, v2
	v_mov_b32_e32 v15, v2
	v_mov_b32_e32 v16, v2
	v_mov_b32_e32 v17, v2
	v_mov_b32_e32 v26, v2
	v_mov_b32_e32 v27, v2
	v_mov_b32_e32 v28, v2
	v_mov_b32_e32 v29, v2
	v_mov_b32_e32 v30, v2
	v_mov_b32_e32 v31, v2
	v_mov_b32_e32 v32, v2
	v_mov_b32_e32 v33, v2
	v_mov_b32_e32 v42, v2
	v_mov_b32_e32 v43, v2
	v_mov_b32_e32 v44, v2
	v_mov_b32_e32 v45, v2
	v_mov_b32_e32 v46, v2
	v_mov_b32_e32 v47, v2
	v_mov_b32_e32 v48, v2
	v_mov_b32_e32 v49, v2
	v_mov_b32_e32 v58, v2
	v_mov_b32_e32 v59, v2
	v_mov_b32_e32 v60, v2
	v_mov_b32_e32 v61, v2
	v_mov_b32_e32 v62, v2
	v_mov_b32_e32 v63, v2
	v_mov_b32_e32 v64, v2
	v_mov_b32_e32 v65, v2
	v_mov_b32_e32 v66, v2
	v_mov_b32_e32 v67, v2
	v_mov_b32_e32 v68, v2
	v_mov_b32_e32 v69, v2
	v_mov_b32_e32 v70, v2
	v_mov_b32_e32 v71, v2
	v_mov_b32_e32 v72, v2
	v_mov_b32_e32 v73, v2
	v_mov_b32_e32 v82, v2
	v_mov_b32_e32 v83, v2
	v_mov_b32_e32 v84, v2
	v_mov_b32_e32 v85, v2
	v_mov_b32_e32 v86, v2
	v_mov_b32_e32 v87, v2
	v_mov_b32_e32 v88, v2
	v_mov_b32_e32 v89, v2
	v_mov_b32_e32 v98, v2
	v_mov_b32_e32 v99, v2
	v_mov_b32_e32 v100, v2
	v_mov_b32_e32 v101, v2
	v_mov_b32_e32 v102, v2
	v_mov_b32_e32 v103, v2
	v_mov_b32_e32 v104, v2
	v_mov_b32_e32 v105, v2
	v_mov_b32_e32 v114, v2
	v_mov_b32_e32 v115, v2
	v_mov_b32_e32 v116, v2
	v_mov_b32_e32 v117, v2
	v_mov_b32_e32 v118, v2
	v_mov_b32_e32 v119, v2
	v_mov_b32_e32 v120, v2
	v_mov_b32_e32 v121, v2
	v_mov_b32_e32 v74, v2
	v_mov_b32_e32 v75, v2
	v_mov_b32_e32 v76, v2
	v_mov_b32_e32 v77, v2
	v_mov_b32_e32 v78, v2
	v_mov_b32_e32 v79, v2
	v_mov_b32_e32 v80, v2
	v_mov_b32_e32 v81, v2
	v_mov_b32_e32 v90, v2
	v_mov_b32_e32 v91, v2
	v_mov_b32_e32 v92, v2
	v_mov_b32_e32 v93, v2
	v_mov_b32_e32 v94, v2
	v_mov_b32_e32 v95, v2
	v_mov_b32_e32 v96, v2
	v_mov_b32_e32 v97, v2
	v_mov_b32_e32 v106, v2
	v_mov_b32_e32 v107, v2
	v_mov_b32_e32 v108, v2
	v_mov_b32_e32 v109, v2
	v_mov_b32_e32 v110, v2
	v_mov_b32_e32 v111, v2
	v_mov_b32_e32 v112, v2
	v_mov_b32_e32 v113, v2
	v_mov_b32_e32 v122, v2
	v_mov_b32_e32 v123, v2
	v_mov_b32_e32 v124, v2
	v_mov_b32_e32 v125, v2
	v_mov_b32_e32 v126, v2
	v_mov_b32_e32 v127, v2
	v_mov_b32_e32 v128, v2
	v_mov_b32_e32 v129, v2

; #define PG8_STAGE(bufoff, gbase, voff) do { _Pragma("unroll") for (int _i = 0; _i < 2; ++_i) \
;         __builtin_amdgcn_global_load_lds((const unsigned*)((const char*)(gbase) + (voff)[_i]), (LAS unsigned*)(lds + (bufoff) + ldsw + _i * 8192), 16, 0, 0); } while (0)
; #define PG8_LDA(dst, b, h) do { _Pragma("unroll") for (int m = 0; m < 4; ++m) _Pragma("unroll") for (int k = 0; k < 2; ++k) dst[m][k] = *(const LAS bf16x8*)(lds + PG8_SA(b, h) + aoff + m * 2048 + k * 1024); } while (0)
; #define PG8_LDB(dst, b, h) do { _Pragma("unroll") for (int n = 0; n < 2; ++n) _Pragma("unroll") for (int k = 0; k < 2; ++k) dst[n][k] = *(const LAS bf16x8*)(lds + PG8_SB(b, h) + boff + n * 2048 + k * 1024); } while (0)
; #define PG8_MMA(ai, bj, At, Bt) do { __builtin_amdgcn_s_setprio(1); _Pragma("unroll") for (int m = 0; m < 4; ++m) _Pragma("unroll") for (int n = 0; n < 2; ++n) _Pragma("unroll") for (int k = 0; k < 2; ++k) \
;         acc[ai][bj][m][n] = __builtin_amdgcn_mfma_f32_16x16x32_bf16(Bt[n][k], At[m][k], acc[ai][bj][m][n], 0, 0, 0); __builtin_amdgcn_s_setprio(0); } while (0)
; #define PG8_WAIT_V(n) asm volatile("s_waitcnt vmcnt(" #n ")" ::: "memory")
; #define PG8_WAIT_L(n) asm volatile("s_waitcnt lgkmcnt(" #n ")" ::: "memory")
; #define PG8_BAR __builtin_amdgcn_s_barrier()
; #define PG8_SCHED __builtin_amdgcn_sched_barrier(0)
; template <class Epi, int AC0, int BC0, int NT0, int AC1, int BC1, int NT1>
; __device__ __forceinline__ void gemm_phase(LAS unsigned char* lds, const Gemm g, const StaticOrder& S, const Epi& E, int tid) {
;     ...
;             PG8_LDB(B0, 1, 0); PG8_LDB(B1, 1, 1); PG8_SCHED; PG8_LDA(At, 1, 0); PG8_STAGE(PG8_SA(0, 1), a2 + hstepA, voffA);
;             PG8_WAIT_V(8); PG8_WAIT_L(0); PG8_BAR; PG8_MMA(0, 0, At, B0); PG8_MMA(0, 1, At, B1); PG8_BAR; PG8_SCHED;
.Lmid_P4:
	s_add_i32 s75, 0, 0x18000
	s_add_i32 s76, 0, 0x1c000
	v_add_u32_e32 v142, s75, v216
	v_add_u32_e32 v158, s76, v216
	ds_read_b128 v[130:133], v142
	ds_read_b128 v[134:137], v142 offset:1024
	ds_read_b128 v[138:141], v142 offset:2048
	ds_read_b128 v[142:145], v142 offset:3072
	ds_read_b128 v[146:149], v158
	ds_read_b128 v[150:153], v158 offset:1024
	ds_read_b128 v[154:157], v158 offset:2048
	ds_read_b128 v[158:161], v158 offset:3072
	s_add_u32 s66, s66, 0x40000
	s_addc_u32 s67, s67, 0
	s_mov_b32 m0, s28
	v_lshl_add_u64 v[226:227], s[66:67], 0, v[186:187]
	ds_read_b128 v[162:165], v220 offset:32768
	ds_read_b128 v[166:169], v220 offset:33792
	ds_read_b128 v[170:173], v220 offset:34816
	ds_read_b128 v[174:177], v220 offset:35840
	ds_read_b128 v[178:181], v220 offset:36864
	ds_read_b128 v[182:185], v220 offset:37888
	ds_read_b128 v[204:207], v220 offset:38912
	ds_read_b128 v[208:211], v220 offset:39936
	global_load_lds_dwordx4 v[226:227], off
	v_lshl_add_u64 v[226:227], s[66:67], 0, v[190:191]
	s_mov_b32 m0, s29
	s_nop 0
	global_load_lds_dwordx4 v[226:227], off
	s_waitcnt vmcnt(8)
	s_waitcnt lgkmcnt(0)
	s_barrier
	s_setprio 1
	s_waitcnt lgkmcnt(0)
	v_mfma_f32_16x16x32_bf16 v[126:129], v[130:133], v[162:165], v[126:129]
	v_mfma_f32_16x16x32_bf16 v[122:125], v[138:141], v[162:165], v[122:125]
	v_mfma_f32_16x16x32_bf16 v[110:113], v[130:133], v[170:173], v[110:113]
	v_mfma_f32_16x16x32_bf16 v[106:109], v[138:141], v[170:173], v[106:109]
	v_mfma_f32_16x16x32_bf16 v[94:97], v[130:133], v[178:181], v[94:97]
	v_mfma_f32_16x16x32_bf16 v[90:93], v[138:141], v[178:181], v[90:93]
	v_mfma_f32_16x16x32_bf16 v[78:81], v[130:133], v[204:207], v[78:81]
	v_mfma_f32_16x16x32_bf16 v[74:77], v[138:141], v[204:207], v[74:77]
	v_mfma_f32_16x16x32_bf16 v[126:129], v[134:137], v[166:169], v[126:129]
	v_mfma_f32_16x16x32_bf16 v[122:125], v[142:145], v[166:169], v[122:125]
	v_mfma_f32_16x16x32_bf16 v[110:113], v[134:137], v[174:177], v[110:113]
	v_mfma_f32_16x16x32_bf16 v[106:109], v[142:145], v[174:177], v[106:109]
	v_mfma_f32_16x16x32_bf16 v[94:97], v[134:137], v[182:185], v[94:97]
	v_mfma_f32_16x16x32_bf16 v[90:93], v[142:145], v[182:185], v[90:93]
	v_mfma_f32_16x16x32_bf16 v[78:81], v[134:137], v[208:211], v[78:81]
	v_mfma_f32_16x16x32_bf16 v[74:77], v[142:145], v[208:211], v[74:77]
	s_setprio 0
	s_setprio 1
	v_mfma_f32_16x16x32_bf16 v[118:121], v[146:149], v[162:165], v[118:121]
	v_mfma_f32_16x16x32_bf16 v[114:117], v[154:157], v[162:165], v[114:117]
	v_mfma_f32_16x16x32_bf16 v[102:105], v[146:149], v[170:173], v[102:105]
	v_mfma_f32_16x16x32_bf16 v[98:101], v[154:157], v[170:173], v[98:101]
	v_mfma_f32_16x16x32_bf16 v[86:89], v[146:149], v[178:181], v[86:89]
	v_mfma_f32_16x16x32_bf16 v[82:85], v[154:157], v[178:181], v[82:85]
	v_mfma_f32_16x16x32_bf16 v[70:73], v[146:149], v[204:207], v[70:73]
	v_mfma_f32_16x16x32_bf16 v[66:69], v[154:157], v[204:207], v[66:69]
	v_mfma_f32_16x16x32_bf16 v[118:121], v[150:153], v[166:169], v[118:121]
	v_mfma_f32_16x16x32_bf16 v[114:117], v[158:161], v[166:169], v[114:117]
	v_mfma_f32_16x16x32_bf16 v[102:105], v[150:153], v[174:177], v[102:105]
	v_mfma_f32_16x16x32_bf16 v[98:101], v[158:161], v[174:177], v[98:101]
	v_mfma_f32_16x16x32_bf16 v[86:89], v[150:153], v[182:185], v[86:89]
	v_mfma_f32_16x16x32_bf16 v[82:85], v[158:161], v[182:185], v[82:85]
	v_mfma_f32_16x16x32_bf16 v[70:73], v[150:153], v[208:211], v[70:73]
	v_mfma_f32_16x16x32_bf16 v[66:69], v[158:161], v[208:211], v[66:69]
	s_setprio 0
	s_barrier
; #define PG8_STAGE(bufoff, gbase, voff) do { _Pragma("unroll") for (int _i = 0; _i < 2; ++_i) \
;         __builtin_amdgcn_global_load_lds((const unsigned*)((const char*)(gbase) + (voff)[_i]), (LAS unsigned*)(lds + (bufoff) + ldsw + _i * 8192), 16, 0, 0); } while (0)
; #define PG8_LDA(dst, b, h) do { _Pragma("unroll") for (int m = 0; m < 4; ++m) _Pragma("unroll") for (int k = 0; k < 2; ++k) dst[m][k] = *(const LAS bf16x8*)(lds + PG8_SA(b, h) + aoff + m * 2048 + k * 1024); } while (0)
; #define PG8_MMA(ai, bj, At, Bt) do { __builtin_amdgcn_s_setprio(1); _Pragma("unroll") for (int m = 0; m < 4; ++m) _Pragma("unroll") for (int n = 0; n < 2; ++n) _Pragma("unroll") for (int k = 0; k < 2; ++k) \
;         acc[ai][bj][m][n] = __builtin_amdgcn_mfma_f32_16x16x32_bf16(Bt[n][k], At[m][k], acc[ai][bj][m][n], 0, 0, 0); __builtin_amdgcn_s_setprio(0); } while (0)
; #define PG8_WAIT_V(n) asm volatile("s_waitcnt vmcnt(" #n ")" ::: "memory")
; #define PG8_WAIT_L(n) asm volatile("s_waitcnt lgkmcnt(" #n ")" ::: "memory")
; #define PG8_BAR __builtin_amdgcn_s_barrier()
; #define PG8_SCHED __builtin_amdgcn_sched_barrier(0)
; template <class Epi, int AC0, int BC0, int NT0, int AC1, int BC1, int NT1>
; __device__ __forceinline__ void gemm_phase(LAS unsigned char* lds, const Gemm g, const StaticOrder& S, const Epi& E, int tid) {
;     ...
;             PG8_LDA(At, 1, 1); PG8_STAGE(PG8_SB(1, 0), b3, voffB); PG8_STAGE(PG8_SB(1, 1), b3 + hstepB, voffB); PG8_STAGE(PG8_SA(1, 0), a3, voffA);
;             PG8_WAIT_V(8); PG8_WAIT_L(0); PG8_BAR; PG8_MMA(1, 0, At, B0); PG8_MMA(1, 1, At, B1); PG8_BAR; PG8_SCHED;
;         }
;         if (wr == 0) PG8_BAR;
	s_add_i32 s66, s75, s25
	v_lshl_add_u64 v[212:213], v[212:213], 0, s[6:7]
	s_mov_b32 m0, s66
	ds_read_b128 v[162:165], v220 offset:49152
	ds_read_b128 v[166:169], v220 offset:50176
	ds_read_b128 v[170:173], v220 offset:51200
	ds_read_b128 v[174:177], v220 offset:52224
	ds_read_b128 v[178:181], v220 offset:53248
	ds_read_b128 v[182:185], v220 offset:54272
	ds_read_b128 v[204:207], v220 offset:55296
	ds_read_b128 v[208:211], v220 offset:56320
	global_load_lds_dwordx4 v[212:213], off
	s_add_i32 m0, s66, 0x2000
	s_add_u32 s20, s20, 0x40080
	v_lshl_add_u64 v[212:213], v[214:215], 0, s[6:7]
	s_addc_u32 s21, s21, 0
	s_add_i32 s66, s76, s25
	global_load_lds_dwordx4 v[212:213], off
	v_lshl_add_u64 v[212:213], s[20:21], 0, v[188:189]
	s_mov_b32 m0, s66
	s_nop 0
	global_load_lds_dwordx4 v[212:213], off
	v_lshl_add_u64 v[212:213], s[20:21], 0, v[192:193]
	s_add_i32 m0, s66, 0x2000
	s_nop 0
	global_load_lds_dwordx4 v[212:213], off
	v_lshl_add_u64 v[212:213], v[222:223], 0, s[6:7]
	s_mov_b32 m0, s35
	s_nop 0
	global_load_lds_dwordx4 v[212:213], off
	v_lshl_add_u64 v[212:213], v[224:225], 0, s[6:7]
	s_mov_b32 m0, s36
	s_nop 0
	global_load_lds_dwordx4 v[212:213], off
	s_waitcnt vmcnt(8)
	s_waitcnt lgkmcnt(0)
	s_barrier
	s_setprio 1
	s_waitcnt lgkmcnt(0)
	v_mfma_f32_16x16x32_bf16 v[62:65], v[130:133], v[162:165], v[62:65]
	v_mfma_f32_16x16x32_bf16 v[58:61], v[138:141], v[162:165], v[58:61]
	v_mfma_f32_16x16x32_bf16 v[46:49], v[130:133], v[170:173], v[46:49]
	v_mfma_f32_16x16x32_bf16 v[42:45], v[138:141], v[170:173], v[42:45]
	v_mfma_f32_16x16x32_bf16 v[30:33], v[130:133], v[178:181], v[30:33]
	v_mfma_f32_16x16x32_bf16 v[26:29], v[138:141], v[178:181], v[26:29]
	v_mfma_f32_16x16x32_bf16 v[14:17], v[130:133], v[204:207], v[14:17]
	v_mfma_f32_16x16x32_bf16 v[10:13], v[138:141], v[204:207], v[10:13]
	v_mfma_f32_16x16x32_bf16 v[62:65], v[134:137], v[166:169], v[62:65]
	v_mfma_f32_16x16x32_bf16 v[58:61], v[142:145], v[166:169], v[58:61]
	v_mfma_f32_16x16x32_bf16 v[46:49], v[134:137], v[174:177], v[46:49]
	v_mfma_f32_16x16x32_bf16 v[42:45], v[142:145], v[174:177], v[42:45]
	v_mfma_f32_16x16x32_bf16 v[30:33], v[134:137], v[182:185], v[30:33]
	v_mfma_f32_16x16x32_bf16 v[26:29], v[142:145], v[182:185], v[26:29]
	v_mfma_f32_16x16x32_bf16 v[14:17], v[134:137], v[208:211], v[14:17]
	v_mfma_f32_16x16x32_bf16 v[10:13], v[142:145], v[208:211], v[10:13]
	s_setprio 0
	s_setprio 1
	v_mfma_f32_16x16x32_bf16 v[54:57], v[146:149], v[162:165], v[54:57]
	v_mfma_f32_16x16x32_bf16 v[50:53], v[154:157], v[162:165], v[50:53]
	v_mfma_f32_16x16x32_bf16 v[38:41], v[146:149], v[170:173], v[38:41]
	v_mfma_f32_16x16x32_bf16 v[34:37], v[154:157], v[170:173], v[34:37]
	v_mfma_f32_16x16x32_bf16 v[22:25], v[146:149], v[178:181], v[22:25]
	v_mfma_f32_16x16x32_bf16 v[18:21], v[154:157], v[178:181], v[18:21]
	v_mfma_f32_16x16x32_bf16 v[6:9], v[146:149], v[204:207], v[6:9]
	v_mfma_f32_16x16x32_bf16 v[2:5], v[154:157], v[204:207], v[2:5]
	v_mfma_f32_16x16x32_bf16 v[54:57], v[150:153], v[166:169], v[54:57]
	v_mfma_f32_16x16x32_bf16 v[50:53], v[158:161], v[166:169], v[50:53]
	v_mfma_f32_16x16x32_bf16 v[38:41], v[150:153], v[174:177], v[38:41]
	v_mfma_f32_16x16x32_bf16 v[34:37], v[158:161], v[174:177], v[34:37]
	v_mfma_f32_16x16x32_bf16 v[22:25], v[150:153], v[182:185], v[22:25]
	v_mfma_f32_16x16x32_bf16 v[18:21], v[158:161], v[182:185], v[18:21]
	v_mfma_f32_16x16x32_bf16 v[6:9], v[150:153], v[208:211], v[6:9]
	v_mfma_f32_16x16x32_bf16 v[2:5], v[158:161], v[208:211], v[2:5]
	s_setprio 0
	s_barrier
	s_add_i32 s73, s73, 2
	s_add_u32 s18, s18, 0x100
	s_addc_u32 s19, s19, 0
	s_add_u32 s15, s15, 0x100
	s_addc_u32 s33, s33, 0
	s_cmp_gt_u32 s73, 13
	s_cbranch_scc0 .LBB0_899
	s_and_b64 vcc, exec, s[10:11]
	s_cbranch_vccz .LBB0_902
	s_barrier

; #define PG8_STAGE(bufoff, gbase, voff) do { _Pragma("unroll") for (int _i = 0; _i < 2; ++_i) \
;         __builtin_amdgcn_global_load_lds((const unsigned*)((const char*)(gbase) + (voff)[_i]), (LAS unsigned*)(lds + (bufoff) + ldsw + _i * 8192), 16, 0, 0); } while (0)
; #define PG8_LDA(dst, b, h) do { _Pragma("unroll") for (int m = 0; m < 4; ++m) _Pragma("unroll") for (int k = 0; k < 2; ++k) dst[m][k] = *(const LAS bf16x8*)(lds + PG8_SA(b, h) + aoff + m * 2048 + k * 1024); } while (0)
; #define PG8_LDB(dst, b, h) do { _Pragma("unroll") for (int n = 0; n < 2; ++n) _Pragma("unroll") for (int k = 0; k < 2; ++k) dst[n][k] = *(const LAS bf16x8*)(lds + PG8_SB(b, h) + boff + n * 2048 + k * 1024); } while (0)
; #define PG8_MMA(ai, bj, At, Bt) do { __builtin_amdgcn_s_setprio(1); _Pragma("unroll") for (int m = 0; m < 4; ++m) _Pragma("unroll") for (int n = 0; n < 2; ++n) _Pragma("unroll") for (int k = 0; k < 2; ++k) \
;         acc[ai][bj][m][n] = __builtin_amdgcn_mfma_f32_16x16x32_bf16(Bt[n][k], At[m][k], acc[ai][bj][m][n], 0, 0, 0); __builtin_amdgcn_s_setprio(0); } while (0)
; #define PG8_WAIT_V(n) asm volatile("s_waitcnt vmcnt(" #n ")" ::: "memory")
; #define PG8_WAIT_L(n) asm volatile("s_waitcnt lgkmcnt(" #n ")" ::: "memory")
; #define PG8_BAR __builtin_amdgcn_s_barrier()
; template <class Epi, int AC0, int BC0, int NT0, int AC1, int BC1, int NT1>
; __device__ __forceinline__ void gemm_phase(LAS unsigned char* lds, const Gemm g, const StaticOrder& S, const Epi& E, int tid) {
;     ...
;         for (int t = 0; t < nt; t += 2) {
;             const bool last = (t == nt - 2);
;             const char* a1 = cA + (size_t)(t + 1) * kstep;
;             const char* a2 = last ? nA : cA + (size_t)(t + 2) * kstep; const char* b2 = last ? nB : cB + (size_t)(t + 2) * kstep;
;             const char* a3 = a2 + kstep; const char* b3 = b2 + kstep;
;             PG8_LDB(B0, 0, 0); PG8_LDB(B1, 0, 1); PG8_SCHED; PG8_LDA(At, 0, 0); PG8_STAGE(PG8_SA(1, 1), a1 + hstepA, voffA);
;             PG8_WAIT_V(8); PG8_WAIT_L(0); PG8_BAR; PG8_MMA(0, 0, At, B0); PG8_MMA(0, 1, At, B1); PG8_BAR; PG8_SCHED;
;             PG8_LDA(At, 0, 1); PG8_STAGE(PG8_SB(0, 0), b2, voffB); PG8_STAGE(PG8_SB(0, 1), b2 + hstepB, voffB); PG8_STAGE(PG8_SA(0, 0), a2, voffA);
;             PG8_WAIT_V(8); PG8_WAIT_L(0); PG8_BAR; PG8_MMA(1, 0, At, B0); PG8_MMA(1, 1, At, B1); PG8_BAR; PG8_SCHED;
.Lpeel_P5:
	ds_read_b128 v[128:131], v231
	ds_read_b128 v[132:135], v231 offset:1024
	ds_read_b128 v[136:139], v231 offset:2048
	ds_read_b128 v[140:143], v231 offset:3072
	ds_read_b128 v[144:147], v232
	ds_read_b128 v[148:151], v232 offset:1024
	ds_read_b128 v[152:155], v232 offset:2048
	ds_read_b128 v[156:159], v232 offset:3072
	s_add_u32 s20, s18, 0x100
	s_addc_u32 s21, s19, 0
	s_cmp_eq_u32 s33, s50
	s_cselect_b32 s25, s5, s21
	s_cselect_b32 s24, s4, s20
	s_cselect_b32 s23, s15, s47
	s_cselect_b32 s22, s14, s46
	v_lshl_add_u64 v[206:207], s[18:19], 0, v[200:201]
	s_add_i32 m0, s28, 0xc000
	ds_read_b128 v[160:163], v233
	ds_read_b128 v[164:167], v233 offset:1024
	ds_read_b128 v[168:171], v233 offset:2048
	ds_read_b128 v[172:175], v233 offset:3072
	ds_read_b128 v[176:179], v233 offset:4096
	ds_read_b128 v[180:183], v233 offset:5120
	ds_read_b128 v[184:187], v233 offset:6144
	ds_read_b128 v[188:191], v233 offset:7168
	global_load_lds_dwordx4 v[206:207], off
	v_lshl_add_u64 v[206:207], s[18:19], 0, v[202:203]
	s_add_i32 m0, s28, 0xe000
	s_nop 0
	global_load_lds_dwordx4 v[206:207], off
	s_waitcnt vmcnt(8)
	s_waitcnt lgkmcnt(0)
	s_barrier
	s_setprio 1
	s_waitcnt lgkmcnt(0)
	v_mfma_f32_16x16x32_bf16 v[124:127], v[128:131], v[160:163], 0
	v_mfma_f32_16x16x32_bf16 v[120:123], v[136:139], v[160:163], 0
	v_mfma_f32_16x16x32_bf16 v[116:119], v[128:131], v[168:171], 0
	v_mfma_f32_16x16x32_bf16 v[112:115], v[136:139], v[168:171], 0
	v_mfma_f32_16x16x32_bf16 v[100:103], v[128:131], v[176:179], 0
	v_mfma_f32_16x16x32_bf16 v[96:99], v[136:139], v[176:179], 0
	v_mfma_f32_16x16x32_bf16 v[84:87], v[128:131], v[184:187], 0
	v_mfma_f32_16x16x32_bf16 v[80:83], v[136:139], v[184:187], 0
	v_mfma_f32_16x16x32_bf16 v[124:127], v[132:135], v[164:167], v[124:127]
	v_mfma_f32_16x16x32_bf16 v[120:123], v[140:143], v[164:167], v[120:123]
	v_mfma_f32_16x16x32_bf16 v[116:119], v[132:135], v[172:175], v[116:119]
	v_mfma_f32_16x16x32_bf16 v[112:115], v[140:143], v[172:175], v[112:115]
	v_mfma_f32_16x16x32_bf16 v[100:103], v[132:135], v[180:183], v[100:103]
	v_mfma_f32_16x16x32_bf16 v[96:99], v[140:143], v[180:183], v[96:99]
	v_mfma_f32_16x16x32_bf16 v[84:87], v[132:135], v[188:191], v[84:87]
	v_mfma_f32_16x16x32_bf16 v[80:83], v[140:143], v[188:191], v[80:83]
	s_setprio 0
	s_setprio 1
	v_mfma_f32_16x16x32_bf16 v[108:111], v[144:147], v[160:163], 0
	v_mfma_f32_16x16x32_bf16 v[104:107], v[152:155], v[160:163], 0
	v_mfma_f32_16x16x32_bf16 v[92:95], v[144:147], v[168:171], 0
	v_mfma_f32_16x16x32_bf16 v[88:91], v[152:155], v[168:171], 0
	v_mfma_f32_16x16x32_bf16 v[76:79], v[144:147], v[176:179], 0
	v_mfma_f32_16x16x32_bf16 v[72:75], v[152:155], v[176:179], 0
	v_mfma_f32_16x16x32_bf16 v[68:71], v[144:147], v[184:187], 0
	v_mfma_f32_16x16x32_bf16 v[64:67], v[152:155], v[184:187], 0
	v_mfma_f32_16x16x32_bf16 v[108:111], v[148:151], v[164:167], v[108:111]
	v_mfma_f32_16x16x32_bf16 v[104:107], v[156:159], v[164:167], v[104:107]
	v_mfma_f32_16x16x32_bf16 v[92:95], v[148:151], v[172:175], v[92:95]
	v_mfma_f32_16x16x32_bf16 v[88:91], v[156:159], v[172:175], v[88:91]
	v_mfma_f32_16x16x32_bf16 v[76:79], v[148:151], v[180:183], v[76:79]
	v_mfma_f32_16x16x32_bf16 v[72:75], v[156:159], v[180:183], v[72:75]
	v_mfma_f32_16x16x32_bf16 v[68:71], v[148:151], v[188:191], v[68:71]
	v_mfma_f32_16x16x32_bf16 v[64:67], v[156:159], v[188:191], v[64:67]
	s_setprio 0
	s_barrier
	s_add_i32 s18, s37, s27
	v_lshl_add_u64 v[206:207], s[22:23], 0, v[194:195]
	s_mov_b32 m0, s18
	ds_read_b128 v[160:163], v233 offset:16384
	ds_read_b128 v[164:167], v233 offset:17408
	ds_read_b128 v[168:171], v233 offset:18432
	ds_read_b128 v[172:175], v233 offset:19456
	ds_read_b128 v[176:179], v233 offset:20480
	ds_read_b128 v[180:183], v233 offset:21504
	ds_read_b128 v[184:187], v233 offset:22528
	ds_read_b128 v[188:191], v233 offset:23552
	global_load_lds_dwordx4 v[206:207], off
	s_add_i32 m0, s18, 0x2000
	s_add_u32 s18, s22, 0x50000
	v_lshl_add_u64 v[208:209], s[22:23], 0, v[198:199]
	s_addc_u32 s19, s23, 0
	s_add_i32 s51, s38, s27
	global_load_lds_dwordx4 v[208:209], off
	v_lshl_add_u64 v[210:211], s[18:19], 0, v[194:195]
	s_mov_b32 m0, s51
	v_lshl_add_u64 v[212:213], s[24:25], 0, v[196:197]
	global_load_lds_dwordx4 v[210:211], off
	v_lshl_add_u64 v[210:211], s[18:19], 0, v[198:199]
	s_add_i32 m0, s51, 0x2000
	s_nop 0
	global_load_lds_dwordx4 v[210:211], off
	v_lshl_add_u64 v[210:211], s[24:25], 0, v[192:193]
	s_mov_b32 m0, s28
	s_nop 0
	global_load_lds_dwordx4 v[210:211], off
	s_mov_b32 m0, s29
	s_nop 0
	global_load_lds_dwordx4 v[212:213], off
	s_waitcnt vmcnt(8)
	s_waitcnt lgkmcnt(0)
	s_barrier
	s_setprio 1
	s_waitcnt lgkmcnt(0)
	v_mfma_f32_16x16x32_bf16 v[60:63], v[128:131], v[160:163], 0
	v_mfma_f32_16x16x32_bf16 v[56:59], v[136:139], v[160:163], 0
	v_mfma_f32_16x16x32_bf16 v[52:55], v[128:131], v[168:171], 0
	v_mfma_f32_16x16x32_bf16 v[48:51], v[136:139], v[168:171], 0
	v_mfma_f32_16x16x32_bf16 v[36:39], v[128:131], v[176:179], 0
	v_mfma_f32_16x16x32_bf16 v[32:35], v[136:139], v[176:179], 0
	v_mfma_f32_16x16x32_bf16 v[20:23], v[128:131], v[184:187], 0
	v_mfma_f32_16x16x32_bf16 v[16:19], v[136:139], v[184:187], 0
	v_mfma_f32_16x16x32_bf16 v[60:63], v[132:135], v[164:167], v[60:63]
	v_mfma_f32_16x16x32_bf16 v[56:59], v[140:143], v[164:167], v[56:59]
	v_mfma_f32_16x16x32_bf16 v[52:55], v[132:135], v[172:175], v[52:55]
	v_mfma_f32_16x16x32_bf16 v[48:51], v[140:143], v[172:175], v[48:51]
	v_mfma_f32_16x16x32_bf16 v[36:39], v[132:135], v[180:183], v[36:39]
	v_mfma_f32_16x16x32_bf16 v[32:35], v[140:143], v[180:183], v[32:35]
	v_mfma_f32_16x16x32_bf16 v[20:23], v[132:135], v[188:191], v[20:23]
	v_mfma_f32_16x16x32_bf16 v[16:19], v[140:143], v[188:191], v[16:19]
	s_setprio 0
	s_setprio 1
	v_mfma_f32_16x16x32_bf16 v[44:47], v[144:147], v[160:163], 0
	v_mfma_f32_16x16x32_bf16 v[40:43], v[152:155], v[160:163], 0
	v_mfma_f32_16x16x32_bf16 v[28:31], v[144:147], v[168:171], 0
	v_mfma_f32_16x16x32_bf16 v[24:27], v[152:155], v[168:171], 0
	v_mfma_f32_16x16x32_bf16 v[12:15], v[144:147], v[176:179], 0
	v_mfma_f32_16x16x32_bf16 v[8:11], v[152:155], v[176:179], 0
	v_mfma_f32_16x16x32_bf16 v[4:7], v[144:147], v[184:187], 0
	v_mfma_f32_16x16x32_bf16 v[0:3], v[152:155], v[184:187], 0
	v_mfma_f32_16x16x32_bf16 v[44:47], v[148:151], v[164:167], v[44:47]
	v_mfma_f32_16x16x32_bf16 v[40:43], v[156:159], v[164:167], v[40:43]
	v_mfma_f32_16x16x32_bf16 v[28:31], v[148:151], v[172:175], v[28:31]
	v_mfma_f32_16x16x32_bf16 v[24:27], v[156:159], v[172:175], v[24:27]
	v_mfma_f32_16x16x32_bf16 v[12:15], v[148:151], v[180:183], v[12:15]
	v_mfma_f32_16x16x32_bf16 v[8:11], v[156:159], v[180:183], v[8:11]
	v_mfma_f32_16x16x32_bf16 v[4:7], v[148:151], v[188:191], v[4:7]
	v_mfma_f32_16x16x32_bf16 v[0:3], v[156:159], v[188:191], v[0:3]
	s_setprio 0
	s_barrier
	s_branch .Lmid_P5

; template <class Epi, int AC0, int BC0, int NT0, int AC1, int BC1, int NT1>
; __device__ __forceinline__ void gemm_phase(LAS unsigned char* lds, const Gemm g, const StaticOrder& S, const Epi& E, int tid) {
;     ...
;         const char* nA = has_next ? PG8_APTR(nxt) : cA; const char* nB = has_next ? PG8_BPTR(nxt) : cB;
;         const int nt = NT0 + cur.seg * (NT1 - NT0);
;         for (int t = 0; t < nt; t += 2) {
;             const bool last = (t == nt - 2);
;             const char* a1 = cA + (size_t)(t + 1) * kstep;
;             const char* a2 = last ? nA : cA + (size_t)(t + 2) * kstep; const char* b2 = last ? nB : cB + (size_t)(t + 2) * kstep;
;             const char* a3 = a2 + kstep; const char* b3 = b2 + kstep;
;     ...
;             for (int a = 0; a < 2; ++a)
; #pragma unroll
;                 for (int b = 0; b < 2; ++b)
; #pragma unroll
;                     for (int m = 0; m < 4; ++m)
; #pragma unroll
;                         for (int n = 0; n < 2; ++n) acc[a][b][m][n] = (f32x4){0.f, 0.f, 0.f, 0.f};
.LBB0_991:
	s_add_u32 s46, s20, 0x100
	s_mul_i32 s33, s16, 12
	s_addc_u32 s47, s21, 0
	s_mov_b32 s50, -2
	s_cmp_lg_u32 s41, 1
	s_cbranch_scc1 .Lpeel_P5
	v_mov_b32_e32 v0, 0
	v_mov_b32_e32 v1, v0
	v_mov_b32_e32 v2, v0
	v_mov_b32_e32 v3, v0
	v_mov_b32_e32 v4, v0
	v_mov_b32_e32 v5, v0
	v_mov_b32_e32 v6, v0
	v_mov_b32_e32 v7, v0
	v_mov_b32_e32 v8, v0
	v_mov_b32_e32 v9, v0
	v_mov_b32_e32 v10, v0
	v_mov_b32_e32 v11, v0
	v_mov_b32_e32 v12, v0
	v_mov_b32_e32 v13, v0
	v_mov_b32_e32 v14, v0
	v_mov_b32_e32 v15, v0
	v_mov_b32_e32 v24, v0
	v_mov_b32_e32 v25, v0
	v_mov_b32_e32 v26, v0
	v_mov_b32_e32 v27, v0
	v_mov_b32_e32 v28, v0
	v_mov_b32_e32 v29, v0
	v_mov_b32_e32 v30, v0
	v_mov_b32_e32 v31, v0
	v_mov_b32_e32 v40, v0
	v_mov_b32_e32 v41, v0
	v_mov_b32_e32 v42, v0
	v_mov_b32_e32 v43, v0
	v_mov_b32_e32 v44, v0
	v_mov_b32_e32 v45, v0
	v_mov_b32_e32 v46, v0
	v_mov_b32_e32 v47, v0
	v_mov_b32_e32 v16, v0
	v_mov_b32_e32 v17, v0
	v_mov_b32_e32 v18, v0
	v_mov_b32_e32 v19, v0
	v_mov_b32_e32 v20, v0
	v_mov_b32_e32 v21, v0
	v_mov_b32_e32 v22, v0
	v_mov_b32_e32 v23, v0
	v_mov_b32_e32 v32, v0
	v_mov_b32_e32 v33, v0
	v_mov_b32_e32 v34, v0
	v_mov_b32_e32 v35, v0
	v_mov_b32_e32 v36, v0
	v_mov_b32_e32 v37, v0
	v_mov_b32_e32 v38, v0
	v_mov_b32_e32 v39, v0
	v_mov_b32_e32 v48, v0
	v_mov_b32_e32 v49, v0
	v_mov_b32_e32 v50, v0
	v_mov_b32_e32 v51, v0
	v_mov_b32_e32 v52, v0
	v_mov_b32_e32 v53, v0
	v_mov_b32_e32 v54, v0
	v_mov_b32_e32 v55, v0
	v_mov_b32_e32 v56, v0
	v_mov_b32_e32 v57, v0
	v_mov_b32_e32 v58, v0
	v_mov_b32_e32 v59, v0
	v_mov_b32_e32 v60, v0
	v_mov_b32_e32 v61, v0
	v_mov_b32_e32 v62, v0
	v_mov_b32_e32 v63, v0
	v_mov_b32_e32 v64, v0
	v_mov_b32_e32 v65, v0
	v_mov_b32_e32 v66, v0
	v_mov_b32_e32 v67, v0
	v_mov_b32_e32 v68, v0
	v_mov_b32_e32 v69, v0
	v_mov_b32_e32 v70, v0
	v_mov_b32_e32 v71, v0
	v_mov_b32_e32 v72, v0
	v_mov_b32_e32 v73, v0
	v_mov_b32_e32 v74, v0
	v_mov_b32_e32 v75, v0
	v_mov_b32_e32 v76, v0
	v_mov_b32_e32 v77, v0
	v_mov_b32_e32 v78, v0
	v_mov_b32_e32 v79, v0
	v_mov_b32_e32 v88, v0
	v_mov_b32_e32 v89, v0
	v_mov_b32_e32 v90, v0
	v_mov_b32_e32 v91, v0
	v_mov_b32_e32 v92, v0
	v_mov_b32_e32 v93, v0
	v_mov_b32_e32 v94, v0
	v_mov_b32_e32 v95, v0
	v_mov_b32_e32 v104, v0
	v_mov_b32_e32 v105, v0
	v_mov_b32_e32 v106, v0
	v_mov_b32_e32 v107, v0
	v_mov_b32_e32 v108, v0
	v_mov_b32_e32 v109, v0
	v_mov_b32_e32 v110, v0
	v_mov_b32_e32 v111, v0
	v_mov_b32_e32 v80, v0
	v_mov_b32_e32 v81, v0
	v_mov_b32_e32 v82, v0
	v_mov_b32_e32 v83, v0
	v_mov_b32_e32 v84, v0
	v_mov_b32_e32 v85, v0
	v_mov_b32_e32 v86, v0
	v_mov_b32_e32 v87, v0
	v_mov_b32_e32 v96, v0
	v_mov_b32_e32 v97, v0
	v_mov_b32_e32 v98, v0
	v_mov_b32_e32 v99, v0
	v_mov_b32_e32 v100, v0
	v_mov_b32_e32 v101, v0
	v_mov_b32_e32 v102, v0
	v_mov_b32_e32 v103, v0
	v_mov_b32_e32 v112, v0
	v_mov_b32_e32 v113, v0
	v_mov_b32_e32 v114, v0
	v_mov_b32_e32 v115, v0
	v_mov_b32_e32 v116, v0
	v_mov_b32_e32 v117, v0
	v_mov_b32_e32 v118, v0
	v_mov_b32_e32 v119, v0
	v_mov_b32_e32 v120, v0
	v_mov_b32_e32 v121, v0
	v_mov_b32_e32 v122, v0
	v_mov_b32_e32 v123, v0
	v_mov_b32_e32 v124, v0
	v_mov_b32_e32 v125, v0
	v_mov_b32_e32 v126, v0
	v_mov_b32_e32 v127, v0

; #define PG8_STAGE(bufoff, gbase, voff) do { _Pragma("unroll") for (int _i = 0; _i < 2; ++_i) \
;         __builtin_amdgcn_global_load_lds((const unsigned*)((const char*)(gbase) + (voff)[_i]), (LAS unsigned*)(lds + (bufoff) + ldsw + _i * 8192), 16, 0, 0); } while (0)
; #define PG8_LDA(dst, b, h) do { _Pragma("unroll") for (int m = 0; m < 4; ++m) _Pragma("unroll") for (int k = 0; k < 2; ++k) dst[m][k] = *(const LAS bf16x8*)(lds + PG8_SA(b, h) + aoff + m * 2048 + k * 1024); } while (0)
; #define PG8_LDB(dst, b, h) do { _Pragma("unroll") for (int n = 0; n < 2; ++n) _Pragma("unroll") for (int k = 0; k < 2; ++k) dst[n][k] = *(const LAS bf16x8*)(lds + PG8_SB(b, h) + boff + n * 2048 + k * 1024); } while (0)
; #define PG8_MMA(ai, bj, At, Bt) do { __builtin_amdgcn_s_setprio(1); _Pragma("unroll") for (int m = 0; m < 4; ++m) _Pragma("unroll") for (int n = 0; n < 2; ++n) _Pragma("unroll") for (int k = 0; k < 2; ++k) \
;         acc[ai][bj][m][n] = __builtin_amdgcn_mfma_f32_16x16x32_bf16(Bt[n][k], At[m][k], acc[ai][bj][m][n], 0, 0, 0); __builtin_amdgcn_s_setprio(0); } while (0)
; #define PG8_WAIT_V(n) asm volatile("s_waitcnt vmcnt(" #n ")" ::: "memory")
; #define PG8_WAIT_L(n) asm volatile("s_waitcnt lgkmcnt(" #n ")" ::: "memory")
; #define PG8_BAR __builtin_amdgcn_s_barrier()
; #define PG8_SCHED __builtin_amdgcn_sched_barrier(0)
; template <class Epi, int AC0, int BC0, int NT0, int AC1, int BC1, int NT1>
; __device__ __forceinline__ void gemm_phase(LAS unsigned char* lds, const Gemm g, const StaticOrder& S, const Epi& E, int tid) {
;     ...
;             PG8_LDB(B0, 1, 0); PG8_LDB(B1, 1, 1); PG8_SCHED; PG8_LDA(At, 1, 0); PG8_STAGE(PG8_SA(0, 1), a2 + hstepA, voffA);
;             PG8_WAIT_V(8); PG8_WAIT_L(0); PG8_BAR; PG8_MMA(0, 0, At, B0); PG8_MMA(0, 1, At, B1); PG8_BAR; PG8_SCHED;
.Lmid_P5:
	s_add_i32 s51, 0, 0x18000
	s_add_i32 s52, 0, 0x1c000
	v_add_u32_e32 v140, s51, v221
	v_add_u32_e32 v156, s52, v221
	ds_read_b128 v[128:131], v140
	ds_read_b128 v[132:135], v140 offset:1024
	ds_read_b128 v[136:139], v140 offset:2048
	ds_read_b128 v[140:143], v140 offset:3072
	ds_read_b128 v[144:147], v156
	ds_read_b128 v[148:151], v156 offset:1024
	ds_read_b128 v[152:155], v156 offset:2048
	ds_read_b128 v[156:159], v156 offset:3072
	s_add_u32 s18, s24, 0x50000
	s_addc_u32 s19, s25, 0
	s_mov_b32 m0, s30
	v_lshl_add_u64 v[214:215], s[18:19], 0, v[192:193]
	ds_read_b128 v[160:163], v233 offset:32768
	ds_read_b128 v[164:167], v233 offset:33792
	ds_read_b128 v[168:171], v233 offset:34816
	ds_read_b128 v[172:175], v233 offset:35840
	ds_read_b128 v[176:179], v233 offset:36864
	ds_read_b128 v[180:183], v233 offset:37888
	ds_read_b128 v[184:187], v233 offset:38912
	ds_read_b128 v[188:191], v233 offset:39936
	global_load_lds_dwordx4 v[214:215], off
	v_lshl_add_u64 v[214:215], s[18:19], 0, v[196:197]
	s_mov_b32 m0, s31
	s_nop 0
	global_load_lds_dwordx4 v[214:215], off
	s_waitcnt vmcnt(8)
	s_waitcnt lgkmcnt(0)
	s_barrier
	s_setprio 1
	s_waitcnt lgkmcnt(0)
	v_mfma_f32_16x16x32_bf16 v[124:127], v[128:131], v[160:163], v[124:127]
	v_mfma_f32_16x16x32_bf16 v[120:123], v[136:139], v[160:163], v[120:123]
	v_mfma_f32_16x16x32_bf16 v[116:119], v[128:131], v[168:171], v[116:119]
	v_mfma_f32_16x16x32_bf16 v[112:115], v[136:139], v[168:171], v[112:115]
	v_mfma_f32_16x16x32_bf16 v[100:103], v[128:131], v[176:179], v[100:103]
	v_mfma_f32_16x16x32_bf16 v[96:99], v[136:139], v[176:179], v[96:99]
	v_mfma_f32_16x16x32_bf16 v[84:87], v[128:131], v[184:187], v[84:87]
	v_mfma_f32_16x16x32_bf16 v[80:83], v[136:139], v[184:187], v[80:83]
	v_mfma_f32_16x16x32_bf16 v[124:127], v[132:135], v[164:167], v[124:127]
	v_mfma_f32_16x16x32_bf16 v[120:123], v[140:143], v[164:167], v[120:123]
	v_mfma_f32_16x16x32_bf16 v[116:119], v[132:135], v[172:175], v[116:119]
	v_mfma_f32_16x16x32_bf16 v[112:115], v[140:143], v[172:175], v[112:115]
	v_mfma_f32_16x16x32_bf16 v[100:103], v[132:135], v[180:183], v[100:103]
	v_mfma_f32_16x16x32_bf16 v[96:99], v[140:143], v[180:183], v[96:99]
	v_mfma_f32_16x16x32_bf16 v[84:87], v[132:135], v[188:191], v[84:87]
	v_mfma_f32_16x16x32_bf16 v[80:83], v[140:143], v[188:191], v[80:83]
	s_setprio 0
	s_setprio 1
	v_mfma_f32_16x16x32_bf16 v[108:111], v[144:147], v[160:163], v[108:111]
	v_mfma_f32_16x16x32_bf16 v[104:107], v[152:155], v[160:163], v[104:107]
	v_mfma_f32_16x16x32_bf16 v[92:95], v[144:147], v[168:171], v[92:95]
	v_mfma_f32_16x16x32_bf16 v[88:91], v[152:155], v[168:171], v[88:91]
	v_mfma_f32_16x16x32_bf16 v[76:79], v[144:147], v[176:179], v[76:79]
	v_mfma_f32_16x16x32_bf16 v[72:75], v[152:155], v[176:179], v[72:75]
	v_mfma_f32_16x16x32_bf16 v[68:71], v[144:147], v[184:187], v[68:71]
	v_mfma_f32_16x16x32_bf16 v[64:67], v[152:155], v[184:187], v[64:67]
	v_mfma_f32_16x16x32_bf16 v[108:111], v[148:151], v[164:167], v[108:111]
	v_mfma_f32_16x16x32_bf16 v[104:107], v[156:159], v[164:167], v[104:107]
	v_mfma_f32_16x16x32_bf16 v[92:95], v[148:151], v[172:175], v[92:95]
	v_mfma_f32_16x16x32_bf16 v[88:91], v[156:159], v[172:175], v[88:91]
	v_mfma_f32_16x16x32_bf16 v[76:79], v[148:151], v[180:183], v[76:79]
	v_mfma_f32_16x16x32_bf16 v[72:75], v[156:159], v[180:183], v[72:75]
	v_mfma_f32_16x16x32_bf16 v[68:71], v[148:151], v[188:191], v[68:71]
	v_mfma_f32_16x16x32_bf16 v[64:67], v[156:159], v[188:191], v[64:67]
	s_setprio 0
	s_barrier
; #define PG8_STAGE(bufoff, gbase, voff) do { _Pragma("unroll") for (int _i = 0; _i < 2; ++_i) \
;         __builtin_amdgcn_global_load_lds((const unsigned*)((const char*)(gbase) + (voff)[_i]), (LAS unsigned*)(lds + (bufoff) + ldsw + _i * 8192), 16, 0, 0); } while (0)
; #define PG8_LDA(dst, b, h) do { _Pragma("unroll") for (int m = 0; m < 4; ++m) _Pragma("unroll") for (int k = 0; k < 2; ++k) dst[m][k] = *(const LAS bf16x8*)(lds + PG8_SA(b, h) + aoff + m * 2048 + k * 1024); } while (0)
; #define PG8_MMA(ai, bj, At, Bt) do { __builtin_amdgcn_s_setprio(1); _Pragma("unroll") for (int m = 0; m < 4; ++m) _Pragma("unroll") for (int n = 0; n < 2; ++n) _Pragma("unroll") for (int k = 0; k < 2; ++k) \
;         acc[ai][bj][m][n] = __builtin_amdgcn_mfma_f32_16x16x32_bf16(Bt[n][k], At[m][k], acc[ai][bj][m][n], 0, 0, 0); __builtin_amdgcn_s_setprio(0); } while (0)
; #define PG8_WAIT_V(n) asm volatile("s_waitcnt vmcnt(" #n ")" ::: "memory")
; #define PG8_WAIT_L(n) asm volatile("s_waitcnt lgkmcnt(" #n ")" ::: "memory")
; #define PG8_BAR __builtin_amdgcn_s_barrier()
; #define PG8_SCHED __builtin_amdgcn_sched_barrier(0)
; template <class Epi, int AC0, int BC0, int NT0, int AC1, int BC1, int NT1>
; __device__ __forceinline__ void gemm_phase(LAS unsigned char* lds, const Gemm g, const StaticOrder& S, const Epi& E, int tid) {
;     ...
;             PG8_LDA(At, 1, 1); PG8_STAGE(PG8_SB(1, 0), b3, voffB); PG8_STAGE(PG8_SB(1, 1), b3 + hstepB, voffB); PG8_STAGE(PG8_SA(1, 0), a3, voffA);
;             PG8_WAIT_V(8); PG8_WAIT_L(0); PG8_BAR; PG8_MMA(1, 0, At, B0); PG8_MMA(1, 1, At, B1); PG8_BAR; PG8_SCHED;
;         }
;         if (wr == 0) PG8_BAR;
	s_add_i32 s18, s51, s27
	v_lshl_add_u64 v[206:207], v[206:207], 0, s[12:13]
	s_mov_b32 m0, s18
	ds_read_b128 v[160:163], v233 offset:49152
	ds_read_b128 v[164:167], v233 offset:50176
	ds_read_b128 v[168:171], v233 offset:51200
	ds_read_b128 v[172:175], v233 offset:52224
	ds_read_b128 v[176:179], v233 offset:53248
	ds_read_b128 v[180:183], v233 offset:54272
	ds_read_b128 v[184:187], v233 offset:55296
	ds_read_b128 v[188:191], v233 offset:56320
	global_load_lds_dwordx4 v[206:207], off
	s_add_i32 m0, s18, 0x2000
	s_add_u32 s18, s22, 0x50080
	v_lshl_add_u64 v[206:207], v[208:209], 0, s[12:13]
	s_addc_u32 s19, s23, 0
	s_add_i32 s22, s52, s27
	global_load_lds_dwordx4 v[206:207], off
	v_lshl_add_u64 v[206:207], s[18:19], 0, v[194:195]
	s_mov_b32 m0, s22
	s_nop 0
	global_load_lds_dwordx4 v[206:207], off
	v_lshl_add_u64 v[206:207], s[18:19], 0, v[198:199]
	s_add_i32 m0, s22, 0x2000
	s_nop 0
	global_load_lds_dwordx4 v[206:207], off
	v_lshl_add_u64 v[206:207], v[210:211], 0, s[12:13]
	s_mov_b32 m0, s34
	s_nop 0
	global_load_lds_dwordx4 v[206:207], off
	v_lshl_add_u64 v[206:207], v[212:213], 0, s[12:13]
	s_mov_b32 m0, s35
	s_nop 0
	global_load_lds_dwordx4 v[206:207], off
	s_waitcnt vmcnt(8)
	s_waitcnt lgkmcnt(0)
	s_barrier
	s_setprio 1
	s_waitcnt lgkmcnt(0)
	v_mfma_f32_16x16x32_bf16 v[60:63], v[128:131], v[160:163], v[60:63]
	v_mfma_f32_16x16x32_bf16 v[56:59], v[136:139], v[160:163], v[56:59]
	v_mfma_f32_16x16x32_bf16 v[52:55], v[128:131], v[168:171], v[52:55]
	v_mfma_f32_16x16x32_bf16 v[48:51], v[136:139], v[168:171], v[48:51]
	v_mfma_f32_16x16x32_bf16 v[36:39], v[128:131], v[176:179], v[36:39]
	v_mfma_f32_16x16x32_bf16 v[32:35], v[136:139], v[176:179], v[32:35]
	v_mfma_f32_16x16x32_bf16 v[20:23], v[128:131], v[184:187], v[20:23]
	v_mfma_f32_16x16x32_bf16 v[16:19], v[136:139], v[184:187], v[16:19]
	v_mfma_f32_16x16x32_bf16 v[60:63], v[132:135], v[164:167], v[60:63]
	v_mfma_f32_16x16x32_bf16 v[56:59], v[140:143], v[164:167], v[56:59]
	v_mfma_f32_16x16x32_bf16 v[52:55], v[132:135], v[172:175], v[52:55]
	v_mfma_f32_16x16x32_bf16 v[48:51], v[140:143], v[172:175], v[48:51]
	v_mfma_f32_16x16x32_bf16 v[36:39], v[132:135], v[180:183], v[36:39]
	v_mfma_f32_16x16x32_bf16 v[32:35], v[140:143], v[180:183], v[32:35]
	v_mfma_f32_16x16x32_bf16 v[20:23], v[132:135], v[188:191], v[20:23]
	v_mfma_f32_16x16x32_bf16 v[16:19], v[140:143], v[188:191], v[16:19]
	s_setprio 0
	s_setprio 1
	v_mfma_f32_16x16x32_bf16 v[44:47], v[144:147], v[160:163], v[44:47]
	v_mfma_f32_16x16x32_bf16 v[40:43], v[152:155], v[160:163], v[40:43]
	v_mfma_f32_16x16x32_bf16 v[28:31], v[144:147], v[168:171], v[28:31]
	v_mfma_f32_16x16x32_bf16 v[24:27], v[152:155], v[168:171], v[24:27]
	v_mfma_f32_16x16x32_bf16 v[12:15], v[144:147], v[176:179], v[12:15]
	v_mfma_f32_16x16x32_bf16 v[8:11], v[152:155], v[176:179], v[8:11]
	v_mfma_f32_16x16x32_bf16 v[4:7], v[144:147], v[184:187], v[4:7]
	v_mfma_f32_16x16x32_bf16 v[0:3], v[152:155], v[184:187], v[0:3]
	v_mfma_f32_16x16x32_bf16 v[44:47], v[148:151], v[164:167], v[44:47]
	v_mfma_f32_16x16x32_bf16 v[40:43], v[156:159], v[164:167], v[40:43]
	v_mfma_f32_16x16x32_bf16 v[28:31], v[148:151], v[172:175], v[28:31]
	v_mfma_f32_16x16x32_bf16 v[24:27], v[156:159], v[172:175], v[24:27]
	v_mfma_f32_16x16x32_bf16 v[12:15], v[148:151], v[180:183], v[12:15]
	v_mfma_f32_16x16x32_bf16 v[8:11], v[156:159], v[180:183], v[8:11]
	v_mfma_f32_16x16x32_bf16 v[4:7], v[148:151], v[188:191], v[4:7]
	v_mfma_f32_16x16x32_bf16 v[0:3], v[156:159], v[188:191], v[0:3]
	s_setprio 0
	s_barrier
	s_add_i32 s50, s50, 2
	s_add_u32 s46, s46, 0x100
	s_addc_u32 s47, s47, 0
	s_cmp_gt_i32 s50, s33
	s_mov_b64 s[18:19], s[20:21]
	s_cbranch_scc0 .LBB0_992
	s_and_b64 vcc, exec, s[10:11]
	s_cbranch_vccz .LBB0_995
	s_barrier
